# input pointers kept in VGPR lanes (written once at entry from the kernel arguments) instead of re-read from the per-workgroup table at each phase start
# speedup vs baseline: 1.0367x; 1.0039x over previous
_Z14fwd_megakernel4Args:
	s_load_dwordx16 s[4:19], s[0:1], 0x0
	s_load_dwordx16 s[36:51], s[0:1], 0x40
	s_load_dwordx16 s[60:75], s[0:1], 0x80
	s_load_dwordx16 s[76:91], s[0:1], 0xc0
	s_load_dwordx2 s[92:93], s[0:1], 0x100
	s_waitcnt lgkmcnt(0)
	v_writelane_b32 v247, s4, 0
	v_writelane_b32 v247, s5, 1
	v_writelane_b32 v247, s6, 2
	v_writelane_b32 v247, s7, 3
	v_writelane_b32 v247, s8, 4
	v_writelane_b32 v247, s9, 5
	v_writelane_b32 v247, s10, 6
	v_writelane_b32 v247, s11, 7
	v_writelane_b32 v247, s12, 8
	v_writelane_b32 v247, s13, 9
	v_writelane_b32 v247, s14, 10
	v_writelane_b32 v247, s15, 11
	v_writelane_b32 v247, s16, 12
	v_writelane_b32 v247, s17, 13
	v_writelane_b32 v247, s18, 14
	v_writelane_b32 v247, s19, 15
	v_writelane_b32 v247, s36, 16
	v_writelane_b32 v247, s37, 17
	v_writelane_b32 v247, s38, 18
	v_writelane_b32 v247, s39, 19
	v_writelane_b32 v247, s40, 20
	v_writelane_b32 v247, s41, 21
	v_writelane_b32 v247, s42, 22
	v_writelane_b32 v247, s43, 23
	v_writelane_b32 v247, s44, 24
	v_writelane_b32 v247, s45, 25
	v_writelane_b32 v247, s46, 26
	v_writelane_b32 v247, s47, 27
	v_writelane_b32 v247, s48, 28
	v_writelane_b32 v247, s49, 29
	v_writelane_b32 v247, s50, 30
	v_writelane_b32 v247, s51, 31
	v_writelane_b32 v247, s60, 32
	v_writelane_b32 v247, s61, 33
	v_writelane_b32 v247, s62, 34
	v_writelane_b32 v247, s63, 35
	v_writelane_b32 v247, s64, 36
	v_writelane_b32 v247, s65, 37
	v_writelane_b32 v247, s66, 38
	v_writelane_b32 v247, s67, 39
	v_writelane_b32 v247, s68, 40
	v_writelane_b32 v247, s69, 41
	v_writelane_b32 v247, s70, 42
	v_writelane_b32 v247, s71, 43
	v_writelane_b32 v247, s72, 44
	v_writelane_b32 v247, s73, 45
	v_writelane_b32 v247, s74, 46
	v_writelane_b32 v247, s75, 47
	v_writelane_b32 v247, s76, 48
	v_writelane_b32 v247, s77, 49
	v_writelane_b32 v247, s78, 50
	v_writelane_b32 v247, s79, 51
	v_writelane_b32 v247, s80, 52
	v_writelane_b32 v247, s81, 53
	v_writelane_b32 v247, s82, 54
	v_writelane_b32 v247, s83, 55
	v_writelane_b32 v247, s84, 56
	v_writelane_b32 v247, s85, 57
	v_writelane_b32 v247, s86, 58
	v_writelane_b32 v247, s87, 59
	v_writelane_b32 v247, s88, 60
	v_writelane_b32 v247, s89, 61
	v_writelane_b32 v247, s90, 62
	v_writelane_b32 v247, s91, 63
	v_writelane_b32 v246, s88, 20
	v_writelane_b32 v246, s89, 21
	v_writelane_b32 v246, s38, 22
	v_writelane_b32 v246, s39, 23
	v_writelane_b32 v246, s92, 24
	v_writelane_b32 v246, s93, 25
	s_load_dwordx2 s[56:57], s[0:1], 0x120
	s_add_u32 s20, s0, 0x120
	s_addc_u32 s21, s1, 0
	v_and_b32_e32 v1, 0x3ff, v0
	s_mov_b32 s95, s2
	s_waitcnt lgkmcnt(0)
	s_and_b32 s4, s56, 7
	v_readfirstlane_b32 s93, v1
	s_mov_b32 s3, 0
	s_cmp_lg_u32 s4, 0
	s_mov_b32 s24, s2
	s_cbranch_scc1 .LBB0_2
	s_ashr_i32 s5, s2, 31
	s_lshr_b32 s5, s5, 29
	s_add_i32 s5, s2, s5
	s_and_b32 s6, s5, -8
	s_ashr_i32 s4, s56, 3
	s_sub_i32 s6, s2, s6
	s_mul_i32 s4, s4, s6
	s_ashr_i32 s5, s5, 3
	s_add_i32 s24, s4, s5

.LBB0_29:
	s_lshr_b32 s94, s93, 6
	s_lshl_b32 s0, s24, 3
	s_add_i32 s8, s0, s94
	s_lshl_b32 s3, s56, 3
	s_lshl_b32 s66, s56, 9
	s_add_u32 s6, s54, 0x500000
	s_addc_u32 s7, s55, 0
	s_add_u32 s64, s54, 0x900000
	s_addc_u32 s65, s55, 0
	s_add_u32 s60, s54, 0xb00000
	s_addc_u32 s61, s55, 0
	s_add_u32 s50, s54, 0x1300000
	s_addc_u32 s51, s55, 0
	s_cmp_lt_i32 s40, 1
	v_writelane_b32 v246, s24, 6
	s_cselect_b64 s[4:5], -1, 0
	s_cmp_gt_i32 s40, 0
	v_writelane_b32 v246, s0, 7
	s_cselect_b64 s[0:1], -1, 0
	s_cmp_lt_i32 s41, 1
	s_cselect_b64 s[10:11], -1, 0
	s_or_b64 s[0:1], s[10:11], s[0:1]
	s_and_b64 vcc, exec, s[0:1]
	s_cbranch_vccnz .LBB0_71
	v_mov_b32_e32 v1, 0
	v_mbcnt_lo_u32_b32 v163, -1, 0
	v_mbcnt_hi_u32_b32 v163, -1, v163
	s_cmpk_gt_i32 s8, 0x14ff
	s_waitcnt vmcnt(3)
	v_readlane_b32 s13, v247, 29
	v_readlane_b32 s12, v247, 28
	s_waitcnt vmcnt(2)
	v_readlane_b32 s11, v247, 37
	v_readlane_b32 s10, v247, 36
	s_waitcnt vmcnt(1)
	v_readlane_b32 s15, v247, 25
	v_readlane_b32 s14, v247, 24
	s_waitcnt vmcnt(0)
	v_readlane_b32 s17, v247, 27
	v_readlane_b32 s16, v247, 26
	v_lshrrev_b32_e32 v3, 3, v163
	v_and_b32_e32 v2, 7, v163
	v_lshlrev_b32_e32 v4, 4, v2
	s_lshl_b32 s18, s94, 14
	v_mul_u32_u24_e32 v5, 33, v3
	v_lshl_add_u32 v5, v2, 2, v5
	v_lshl_add_u32 v5, v5, 2, s18
	v_mul_u32_u24_e32 v6, 0x108, v2
	v_add_u32_e32 v6, v6, v3
	v_lshl_add_u32 v6, v6, 2, s18
	s_lshr_b32 s18, s8, 3
	s_cmp_lg_u32 s56, 0x100
	s_cbranch_scc1 .Ltr_generic
	s_cmp_lt_u32 s18, 0xc0
	s_cbranch_scc0 .Ltr_free
	s_mul_i32 s0, s18, 13
	s_add_i32 s9, s0, 13
	s_branch .Ltr_dealt

.Ltr_done:
.LBB0_45:
	s_barrier
	s_and_b32 s0, s93, 0xffffffc0
	v_readlane_b32 s1, v246, 6
	s_cmpk_gt_i32 s1, 0xbf
	v_add_u32_e32 v160, s0, v163
	s_waitcnt vmcnt(3)
	v_readlane_b32 s1, v247, 21
	v_readlane_b32 s0, v247, 20
	s_waitcnt vmcnt(2)
	v_readlane_b32 s13, v247, 23
	v_readlane_b32 s12, v247, 22
	s_waitcnt vmcnt(1)
	v_readlane_b32 s19, v247, 5
	v_readlane_b32 s18, v247, 4
	s_waitcnt vmcnt(0)
	v_readlane_b32 s15, v247, 15
	v_readlane_b32 s14, v247, 14
	s_cbranch_scc1 .LBB0_55
	s_movk_i32 s9, 0x1400
	v_cmp_gt_i32_e32 vcc, s9, v160
	s_and_saveexec_b64 s[16:17], vcc
	s_cbranch_execz .LBB0_49
	s_lshl_b32 s9, s94, 8
	v_ashrrev_i32_e32 v161, 31, v160
	s_add_i32 s9, s9, 0
	s_movk_i32 s20, 0xc000
	v_lshl_add_u64 v[0:1], v[160:161], 2, s[18:19]
	v_lshl_add_u32 v4, v163, 2, s9
	s_mov_b64 s[18:19], 0
	s_movk_i32 s9, 0x1000
	v_mov_b32_e32 v3, 0
	s_mov_b32 s21, -1
	s_mov_b64 s[22:23], 0x800
	s_movk_i32 s24, 0x11ff
	v_mov_b32_e32 v2, v160
	s_mov_b64 s[18:19], 0x1000
	v_lshlrev_b32_e32 v8, 2, v2
	global_load_dword v20, v[0:1], off
	global_load_dword v21, v[0:1], off offset:2048
	v_lshl_add_u64 v[6:7], v[0:1], 0, s[18:19]
	global_load_dword v22, v[6:7], off
	global_load_dword v23, v[6:7], off offset:2048
	v_lshl_add_u64 v[6:7], v[6:7], 0, s[18:19]
	global_load_dword v24, v[6:7], off
	global_load_dword v25, v[6:7], off offset:2048
	v_lshl_add_u64 v[6:7], v[6:7], 0, s[18:19]
	global_load_dword v26, v[6:7], off
	global_load_dword v27, v[6:7], off offset:2048
	global_load_dword v28, v8, s[14:15]
	global_load_dword v29, v8, s[14:15] offset:2048
	s_waitcnt vmcnt(0) lgkmcnt(0)
	v_mul_f32_e32 v30, 0xbfb8aa3b, v20
	v_exp_f32_e32 v30, v30
	s_nop 0
	v_add_f32_e32 v30, 1.0, v30
	v_div_scale_f32 v31, s[26:27], v30, v30, 1.0
	v_rcp_f32_e32 v32, v31
	v_div_scale_f32 v33, vcc, 1.0, v30, 1.0
	v_fma_f32 v34, -v31, v32, 1.0
	v_fmac_f32_e32 v32, v34, v32
	v_mul_f32_e32 v34, v33, v32
	v_fma_f32 v35, -v31, v34, v33
	v_fmac_f32_e32 v34, v35, v32
	v_fma_f32 v31, -v31, v34, v33
	v_div_fmas_f32 v31, v31, v32, v34
	v_div_fixup_f32 v30, v31, v30, 1.0
	v_mul_f32_e32 v20, v20, v30
	ds_write_b32 v4, v20
	v_mul_f32_e32 v38, 0xbfb8aa3b, v21
	v_exp_f32_e32 v38, v38
	s_nop 0
	v_add_f32_e32 v38, 1.0, v38
	v_div_scale_f32 v39, s[26:27], v38, v38, 1.0
	v_rcp_f32_e32 v40, v39
	v_div_scale_f32 v41, vcc, 1.0, v38, 1.0
	v_fma_f32 v42, -v39, v40, 1.0
	v_fmac_f32_e32 v40, v42, v40
	v_mul_f32_e32 v42, v41, v40
	v_fma_f32 v43, -v39, v42, v41
	v_fmac_f32_e32 v42, v43, v40
	v_fma_f32 v39, -v39, v42, v41
	v_div_fmas_f32 v39, v39, v40, v42
	v_div_fixup_f32 v38, v39, v38, 1.0
	v_mul_f32_e32 v21, v21, v38
	ds_write_b32 v4, v21 offset:2048
	v_mul_f32_e32 v46, 0xbfb8aa3b, v22
	v_exp_f32_e32 v46, v46
	s_nop 0
	v_add_f32_e32 v46, 1.0, v46
	v_div_scale_f32 v47, s[26:27], v46, v46, 1.0
	v_rcp_f32_e32 v48, v47
	v_div_scale_f32 v49, vcc, 1.0, v46, 1.0
	v_fma_f32 v50, -v47, v48, 1.0
	v_fmac_f32_e32 v48, v50, v48
	v_mul_f32_e32 v50, v49, v48
	v_fma_f32 v51, -v47, v50, v49
	v_fmac_f32_e32 v50, v51, v48
	v_fma_f32 v47, -v47, v50, v49
	v_div_fmas_f32 v47, v47, v48, v50
	v_div_fixup_f32 v46, v47, v46, 1.0
	v_mul_f32_e32 v22, v22, v46
	ds_write_b32 v4, v22 offset:4096
	v_mul_f32_e32 v54, 0xbfb8aa3b, v23
	v_exp_f32_e32 v54, v54
	s_nop 0
	v_add_f32_e32 v54, 1.0, v54
	v_div_scale_f32 v55, s[26:27], v54, v54, 1.0
	v_rcp_f32_e32 v56, v55
	v_div_scale_f32 v57, vcc, 1.0, v54, 1.0
	v_fma_f32 v58, -v55, v56, 1.0
	v_fmac_f32_e32 v56, v58, v56
	v_mul_f32_e32 v58, v57, v56
	v_fma_f32 v59, -v55, v58, v57
	v_fmac_f32_e32 v58, v59, v56
	v_fma_f32 v55, -v55, v58, v57
	v_div_fmas_f32 v55, v55, v56, v58
	v_div_fixup_f32 v54, v55, v54, 1.0
	v_mul_f32_e32 v23, v23, v54
	ds_write_b32 v4, v23 offset:6144
	v_mul_f32_e32 v62, 0xbfb8aa3b, v24
	v_exp_f32_e32 v62, v62
	s_nop 0
	v_add_f32_e32 v62, 1.0, v62
	v_div_scale_f32 v63, s[26:27], v62, v62, 1.0
	v_rcp_f32_e32 v64, v63
	v_div_scale_f32 v65, vcc, 1.0, v62, 1.0
	v_fma_f32 v66, -v63, v64, 1.0
	v_fmac_f32_e32 v64, v66, v64
	v_mul_f32_e32 v66, v65, v64
	v_fma_f32 v67, -v63, v66, v65
	v_fmac_f32_e32 v66, v67, v64
	v_fma_f32 v63, -v63, v66, v65
	v_div_fmas_f32 v63, v63, v64, v66
	v_div_fixup_f32 v62, v63, v62, 1.0
	v_mul_f32_e32 v24, v24, v62
	ds_write_b32 v4, v24 offset:8192
	v_mul_f32_e32 v70, 0xbfb8aa3b, v25
	v_exp_f32_e32 v70, v70
	s_nop 0
	v_add_f32_e32 v70, 1.0, v70
	v_div_scale_f32 v71, s[26:27], v70, v70, 1.0
	v_rcp_f32_e32 v72, v71
	v_div_scale_f32 v73, vcc, 1.0, v70, 1.0
	v_fma_f32 v74, -v71, v72, 1.0
	v_fmac_f32_e32 v72, v74, v72
	v_mul_f32_e32 v74, v73, v72
	v_fma_f32 v75, -v71, v74, v73
	v_fmac_f32_e32 v74, v75, v72
	v_fma_f32 v71, -v71, v74, v73
	v_div_fmas_f32 v71, v71, v72, v74
	v_div_fixup_f32 v70, v71, v70, 1.0
	v_mul_f32_e32 v25, v25, v70
	ds_write_b32 v4, v25 offset:10240
	v_mul_f32_e32 v78, 0xbfb8aa3b, v26
	v_exp_f32_e32 v78, v78
	s_nop 0
	v_add_f32_e32 v78, 1.0, v78
	v_div_scale_f32 v79, s[26:27], v78, v78, 1.0
	v_rcp_f32_e32 v80, v79
	v_div_scale_f32 v81, vcc, 1.0, v78, 1.0
	v_fma_f32 v82, -v79, v80, 1.0
	v_fmac_f32_e32 v80, v82, v80
	v_mul_f32_e32 v82, v81, v80
	v_fma_f32 v83, -v79, v82, v81
	v_fmac_f32_e32 v82, v83, v80
	v_fma_f32 v79, -v79, v82, v81
	v_div_fmas_f32 v79, v79, v80, v82
	v_div_fixup_f32 v78, v79, v78, 1.0
	v_mul_f32_e32 v26, v26, v78
	ds_write_b32 v4, v26 offset:12288
	v_mul_f32_e32 v86, 0xbfb8aa3b, v27
	v_exp_f32_e32 v86, v86
	s_nop 0
	v_add_f32_e32 v86, 1.0, v86
	v_div_scale_f32 v87, s[26:27], v86, v86, 1.0
	v_rcp_f32_e32 v88, v87
	v_div_scale_f32 v89, vcc, 1.0, v86, 1.0
	v_fma_f32 v90, -v87, v88, 1.0
	v_fmac_f32_e32 v88, v90, v88
	v_mul_f32_e32 v90, v89, v88
	v_fma_f32 v91, -v87, v90, v89
	v_fmac_f32_e32 v90, v91, v88
	v_fma_f32 v87, -v87, v90, v89
	v_div_fmas_f32 v87, v87, v88, v90
	v_div_fixup_f32 v86, v87, v86, 1.0
	v_mul_f32_e32 v27, v27, v86
	ds_write_b32 v4, v27 offset:14336
	v_mul_f32_e32 v94, 0xbfb8aa3b, v28
	v_exp_f32_e32 v94, v94
	s_nop 0
	v_add_f32_e32 v94, 1.0, v94
	v_div_scale_f32 v95, s[26:27], v94, v94, 1.0
	v_rcp_f32_e32 v96, v95
	v_div_scale_f32 v97, vcc, 1.0, v94, 1.0
	v_fma_f32 v98, -v95, v96, 1.0
	v_fmac_f32_e32 v96, v98, v96
	v_mul_f32_e32 v98, v97, v96
	v_fma_f32 v99, -v95, v98, v97
	v_fmac_f32_e32 v98, v99, v96
	v_fma_f32 v95, -v95, v98, v97
	v_div_fmas_f32 v95, v95, v96, v98
	v_div_fixup_f32 v94, v95, v94, 1.0
	v_mul_f32_e32 v28, v28, v94
	ds_write_b32 v4, v28 offset:16384
	v_mul_f32_e32 v102, 0xbfb8aa3b, v29
	v_exp_f32_e32 v102, v102
	s_nop 0
	v_add_f32_e32 v102, 1.0, v102
	v_div_scale_f32 v103, s[26:27], v102, v102, 1.0
	v_rcp_f32_e32 v104, v103
	v_div_scale_f32 v105, vcc, 1.0, v102, 1.0
	v_fma_f32 v106, -v103, v104, 1.0
	v_fmac_f32_e32 v104, v106, v104
	v_mul_f32_e32 v106, v105, v104
	v_fma_f32 v107, -v103, v106, v105
	v_fmac_f32_e32 v106, v107, v104
	v_fma_f32 v103, -v103, v106, v105
	v_div_fmas_f32 v103, v103, v104, v106
	v_div_fixup_f32 v102, v103, v102, 1.0
	v_mul_f32_e32 v29, v29, v102
	ds_write_b32 v4, v29 offset:18432

.LBB0_55:
	v_mov_b32_e32 v0, 0
	v_readlane_b32 s0, v246, 6
	s_waitcnt vmcnt(4)
	v_readlane_b32 s1, v247, 47
	v_lshl_add_u32 v0, s0, 9, v160
	s_mov_b32 s0, 0x11000
	v_cmp_gt_i32_e32 vcc, s0, v0
	v_readlane_b32 s0, v247, 46
	s_waitcnt vmcnt(3)
	v_readlane_b32 s13, v247, 43
	v_readlane_b32 s12, v247, 42
	s_waitcnt vmcnt(2)
	v_readlane_b32 s15, v247, 45
	v_readlane_b32 s14, v247, 44
	s_waitcnt vmcnt(1)
	v_readlane_b32 s17, v247, 49
	v_readlane_b32 s16, v247, 48
	s_waitcnt vmcnt(0)
	v_readlane_b32 s19, v247, 51
	v_readlane_b32 s18, v247, 50
	v_ashrrev_i32_e32 v1, 31, v0
	s_and_saveexec_b64 s[20:21], vcc
	s_cbranch_execz .LBB0_58
	v_lshl_add_u64 v[2:3], v[0:1], 3, s[54:55]
	s_mov_b64 s[22:23], 0x40000
	s_ashr_i32 s67, s66, 31
	s_mov_b32 s28, 0x6dc9c883
	v_and_b32_e32 v4, 63, v163
	v_lshl_add_u64 v[2:3], v[2:3], 0, s[22:23]
	s_lshl_b64 s[22:23], s[66:67], 3
	s_mov_b64 s[26:27], 0
	s_mov_b32 s9, 0x78787879
	s_mov_b32 s29, 0x3fc45f30
	s_mov_b32 s24, 0x10fff
	v_mov_b32_e32 v5, v0

.LBB0_65:
	s_or_b64 exec, exec, s[20:21]
	v_mov_b32_e32 v3, 0
	s_mov_b32 s0, 0x20000
	v_cmp_gt_i32_e32 vcc, s0, v0
	s_waitcnt vmcnt(1)
	v_readlane_b32 s13, v247, 31
	v_readlane_b32 s12, v247, 30
	s_waitcnt vmcnt(0)
	v_readlane_b32 s15, v247, 33
	v_readlane_b32 s14, v247, 32
	s_and_saveexec_b64 s[16:17], vcc
	s_cbranch_execz .LBB0_70
	s_add_u32 s10, s10, 0x1f000
	s_addc_u32 s11, s11, 0
	s_and_b32 s0, s93, 0x3c0
	v_add_u16_e32 v1, s0, v163
	v_readlane_b32 s0, v246, 6
	s_lshl_b32 s0, s0, 9
	s_mov_b64 s[18:19], 0
	v_add_u16_e32 v1, s0, v1
	s_mov_b32 s9, 0xfffe2000
	s_mov_b32 s24, 0xfffe3000
	s_mov_b32 s25, 0xfffe4000
	s_mov_b32 s26, 0xfffe5000
	s_mov_b32 s27, 0xfffe6000
	s_mov_b32 s28, 0xfffe7000
	s_mov_b32 s29, 0xfffe8000
	s_mov_b32 s30, 0xfffe9000
	s_mov_b32 s31, 0xfffea000
	s_mov_b32 s33, 0xfffeb000
	s_mov_b32 s34, 0xfffec000
	s_mov_b32 s35, 0xfffed000
	s_mov_b32 s36, 0xfffee000
	s_mov_b32 s37, 0xfffef000
	s_mov_b32 s38, 0xffff0000
	s_mov_b32 s39, 0xffff1000
	s_mov_b32 s42, 0xffff2000
	s_mov_b32 s43, 0xffff3000
	s_mov_b32 s44, 0xffff4000
	s_mov_b32 s45, 0xffff5000
	s_mov_b32 s46, 0xffff6000
	s_mov_b32 s47, 0xffff7000
	s_movk_i32 s48, 0x8000
	s_movk_i32 s49, 0x9000
	s_movk_i32 s62, 0xa000
	s_movk_i32 s63, 0xb000
	s_movk_i32 s67, 0xc000
	s_movk_i32 s68, 0xd000
	s_movk_i32 s69, 0xe000
	s_movk_i32 s70, 0xf000
	s_mov_b64 s[20:21], 0x20000
	s_mov_b32 s71, 0x1ffff

.LBB0_121:
	s_cmp_lt_i32 s40, 2
	s_cselect_b64 s[10:11], -1, 0
	s_and_b64 s[0:1], s[0:1], s[10:11]
	s_andn2_b64 vcc, exec, s[0:1]
	s_cbranch_vccnz .LBB0_133
	v_mov_b32_e32 v6, 0
	v_mbcnt_lo_u32_b32 v36, -1, 0
	v_mbcnt_hi_u32_b32 v36, -1, v36
	s_cmpk_gt_i32 s8, 0x2fff
	s_waitcnt vmcnt(2)
	v_readlane_b32 s24, v247, 1
	v_readlane_b32 s25, v247, 0
	s_waitcnt vmcnt(1)
	v_readlane_b32 s4, v247, 3
	v_readlane_b32 s5, v247, 2
	s_waitcnt vmcnt(0)
	v_readlane_b32 s1, v247, 17
	v_readlane_b32 s0, v247, 16
	s_cbranch_scc1 .LBB0_133
	v_mbcnt_lo_u32_b32 v0, -1, 0
	v_mbcnt_hi_u32_b32 v0, -1, v0
	v_and_b32_e32 v1, 64, v0
	v_add_u32_e32 v1, 64, v1
	v_xor_b32_e32 v2, 1, v0
	v_cmp_lt_i32_e32 vcc, v2, v1
	s_lshl_b32 s12, s56, 4
	s_add_u32 s33, s5, 0xff000000
	v_cndmask_b32_e32 v2, v0, v2, vcc
	v_lshlrev_b32_e32 v64, 2, v2
	v_xor_b32_e32 v2, 2, v0
	v_cmp_lt_i32_e32 vcc, v2, v1
	v_lshlrev_b32_e32 v38, 2, v36
	s_addc_u32 s36, s4, -1
	v_cndmask_b32_e32 v2, v0, v2, vcc
	v_lshlrev_b32_e32 v65, 2, v2
	v_xor_b32_e32 v2, 4, v0
	v_cmp_lt_i32_e32 vcc, v2, v1
	v_ashrrev_i32_e32 v39, 31, v38
	s_ashr_i32 s9, s8, 31
	v_cndmask_b32_e32 v2, v0, v2, vcc
	v_lshlrev_b32_e32 v66, 2, v2
	v_xor_b32_e32 v2, 8, v0
	v_cmp_lt_i32_e32 vcc, v2, v1
	v_lshl_add_u64 v[40:41], v[38:39], 2, s[0:1]
	s_lshl_b64 s[0:1], s[8:9], 11
	v_cndmask_b32_e32 v2, v0, v2, vcc
	s_add_u32 s16, s54, s0
	v_ashrrev_i32_e32 v37, 31, v36
	v_lshlrev_b32_e32 v67, 2, v2
	v_xor_b32_e32 v2, 16, v0
	s_addc_u32 s17, s55, s1
	s_lshl_b64 s[0:1], s[8:9], 12
	v_cmp_lt_i32_e32 vcc, v2, v1
	v_lshl_add_u64 v[50:51], v[36:37], 4, s[0:1]
	s_add_i32 s0, s94, s3
	v_readlane_b32 s1, v246, 7
	v_cndmask_b32_e32 v2, v0, v2, vcc
	s_add_i32 s0, s0, s1
	v_lshlrev_b32_e32 v68, 2, v2
	v_xor_b32_e32 v2, 32, v0
	s_ashr_i32 s13, s12, 31
	s_ashr_i32 s1, s0, 31
	v_cmp_lt_i32_e32 vcc, v2, v1
	s_lshl_b64 s[18:19], s[12:13], 11
	s_lshl_b64 s[20:21], s[12:13], 12
	s_lshl_b64 s[0:1], s[0:1], 11
	v_cndmask_b32_e32 v0, v0, v2, vcc
	v_add_u32_e32 v42, 0x100, v38
	v_add_u32_e32 v44, 0x200, v38
	v_add_u32_e32 v46, 0x300, v38
	s_add_u32 s22, s54, s0
	s_mov_b32 s15, 0
	v_lshlrev_b32_e32 v69, 2, v0
	v_ashrrev_i32_e32 v43, 31, v42
	v_ashrrev_i32_e32 v45, 31, v44
	v_ashrrev_i32_e32 v47, 31, v46
	v_lshlrev_b64 v[48:49], 1, v[38:39]
	s_addc_u32 s23, s55, s1
	v_mov_b32_e32 v70, 0x358637bd
	s_mov_b32 s9, 0xf800000
	v_mov_b32_e32 v71, 0x260
	v_lshlrev_b64 v[52:53], 2, v[38:39]
	s_mov_b32 s13, 0x4200000
	s_branch .LBB0_125

.LBB0_200:
	s_cmpk_lt_i32 s2, 0x80
	s_cbranch_scc1 .LBB0_206
	v_mov_b32_e32 v1, 0
	s_lshl_b32 s3, s2, 9
	s_and_b32 s4, s93, 0xffffffc0
	s_add_i32 s3, s3, s4
	s_add_i32 s3, s3, 0xffff0000
	s_movk_i32 s5, 0x4000
	v_mbcnt_lo_u32_b32 v2, -1, 0
	v_mbcnt_hi_u32_b32 v2, -1, v2
	s_waitcnt vmcnt(0)
	v_readlane_b32 s9, v247, 53
	v_add_u32_e32 v0, s3, v2
	v_readlane_b32 s8, v247, 52
	v_readlane_b32 s7, v247, 55
	v_readlane_b32 s6, v247, 54
	v_cmp_gt_i32_e32 vcc, s5, v0
	s_and_saveexec_b64 s[4:5], vcc
	s_cbranch_execz .LBB0_205
	v_and_b32_e32 v4, 15, v2
	v_ashrrev_i32_e32 v2, 8, v0
	v_ashrrev_i32_e32 v3, 31, v2
	v_lshlrev_b32_e32 v0, 2, v0
	v_and_b32_e32 v0, 0x3c0, v0
	v_lshlrev_b64 v[6:7], 12, v[2:3]
	v_lshl_or_b32 v6, v0, 2, v6
	v_lshlrev_b64 v[18:19], 13, v[2:3]
	v_lshl_add_u64 v[10:11], s[8:9], 0, v[6:7]
	v_mul_hi_i32_i24_e32 v13, 0x2200, v2
	v_mul_i32_i24_e32 v12, 0x2200, v2
	v_lshl_add_u64 v[24:25], s[6:7], 0, v[6:7]
	v_lshl_or_b32 v18, v4, 3, v18
	s_mov_b64 s[6:7], 0
	s_mov_b32 s3, 0x100000
	s_mov_b32 s10, 0x40000
	s_mov_b64 s[8:9], 0x100
	v_mov_b32_e32 v26, v1
	v_mov_b32_e32 v27, v1
	v_mov_b32_e32 v28, v1
	v_mov_b32_e32 v29, v1
	v_mov_b32_e32 v20, v1
	v_mov_b32_e32 v21, v1
	v_mov_b32_e32 v22, v1
	v_mov_b32_e32 v23, v1
	v_mov_b32_e32 v14, v1
	v_mov_b32_e32 v15, v1
	v_mov_b32_e32 v16, v1
	v_mov_b32_e32 v17, v1
	v_mov_b32_e32 v8, v1
	v_mov_b32_e32 v9, v1
	v_mov_b32_e32 v6, v1
	v_mov_b32_e32 v7, v1

.LBB0_256:
	s_cmp_lt_i32 s40, 4
	s_cselect_b64 s[68:69], -1, 0
	s_add_u32 s48, s54, 0x8a00000
	s_addc_u32 s49, s55, 0
	s_and_b64 s[0:1], s[4:5], s[68:69]
	s_andn2_b64 vcc, exec, s[0:1]
	s_cbranch_vccnz .LBB0_282
	v_mov_b32_e32 v5, 0
	v_mbcnt_lo_u32_b32 v2, -1, 0
	v_mbcnt_hi_u32_b32 v2, -1, v2
	v_readlane_b32 s1, v246, 6
	s_and_b32 s0, s93, 0xffffffc0
	s_lshl_b32 s1, s1, 9
	s_add_i32 s1, s1, s0
	s_mov_b32 s3, 0x30000
	v_add_u32_e32 v22, s1, v2
	v_cmp_gt_i32_e32 vcc, s3, v22
	v_lshlrev_b32_e32 v23, 3, v22
	s_waitcnt vmcnt(0)
	v_readlane_b32 s71, v247, 35
	v_readlane_b32 s70, v247, 34
	s_and_saveexec_b64 s[72:73], vcc
	s_cbranch_execz .LBB0_272
	v_lshlrev_b32_e32 v12, 3, v22
	s_lshl_b32 s3, s56, 12
	s_mov_b64 s[74:75], 0
	s_mov_b32 s24, 0x2aaaaaab
	s_mov_b32 s25, 0xffff4000
	s_movk_i32 s33, 0x1000
	v_mov_b32_e32 v13, 0x7fc
	v_bfrev_b32_e32 v14, 0.5
	v_mov_b32_e32 v15, 0x800
	v_mov_b32_e32 v16, 0x100
	v_mov_b32_e32 v17, 0xfffff800
	v_mov_b32_e32 v18, 0xffffff00
	s_mov_b32 s42, 0xbfff
	s_mov_b32 s43, 0x17ffe
	s_mov_b32 s67, 0x2ffff
	v_mov_b32_e32 v19, v22
	s_branch .LBB0_260

.LBB0_332:
	s_cmp_lt_i32 s40, 5
	s_cselect_b64 s[12:13], -1, 0
	s_and_b64 s[0:1], s[0:1], s[12:13]
	s_andn2_b64 vcc, exec, s[0:1]
	s_cbranch_vccnz .LBB0_378
	v_mov_b32_e32 v153, 0
	s_cmpk_gt_i32 s2, 0xbf
	v_mbcnt_lo_u32_b32 v8, -1, 0
	v_mbcnt_hi_u32_b32 v8, -1, v8
	s_waitcnt vmcnt(0)
	v_readlane_b32 s15, v247, 19
	v_readlane_b32 s14, v247, 18
	s_cbranch_scc1 .LBB0_378
	s_lshl_b32 s3, s94, 10
	v_lshlrev_b32_e32 v12, 4, v8
	v_add_u32_e32 v0, s3, v12
	v_add_u32_e32 v1, 0x2000, v0
	v_ashrrev_i32_e32 v2, 31, v1
	v_lshrrev_b32_e32 v2, 22, v2
	v_add_u32_e32 v2, v1, v2
	v_ashrrev_i32_e32 v9, 10, v2
	v_mul_i32_i24_e32 v2, 0x400, v9
	v_sub_u32_e32 v1, v1, v2
	v_lshrrev_b32_e32 v2, 4, v1
	v_bitop3_b32 v1, v2, v1, 32 bitop3:0x6c
	v_ashrrev_i32_e32 v2, 31, v1
	v_lshrrev_b32_e32 v2, 26, v2
	v_add_u32_e32 v2, v1, v2
	v_ashrrev_i32_e32 v10, 6, v2
	v_lshlrev_b32_e32 v3, 3, v9
	v_and_b32_e32 v2, 0xffc0, v2
	v_and_b32_e32 v3, -16, v3
	v_sub_u32_e32 v1, v1, v2
	v_add_u32_e32 v3, v10, v3
	v_lshrrev_b16_e32 v2, 7, v1
	v_and_b32_e32 v4, 3, v10
	s_mov_b32 s11, 0x1fffe0
	v_lshrrev_b32_e32 v5, 2, v3
	v_lshlrev_b32_e32 v6, 1, v3
	v_and_b32_e32 v2, 1, v2
	v_and_or_b32 v4, v3, s11, v4
	v_and_b32_e32 v5, 4, v5
	v_and_b32_e32 v6, 24, v6
	v_add_u16_e32 v1, v1, v2
	v_mov_b32_e32 v2, 1
	v_or3_b32 v4, v4, v5, v6
	v_lshlrev_b32_e32 v5, 5, v9
	v_ashrrev_i16_sdwa v1, v2, sext(v1) dst_sel:DWORD dst_unused:UNUSED_PAD src0_sel:DWORD src1_sel:BYTE_0
	v_and_b32_e32 v5, 32, v5
	v_bfe_i32 v11, v1, 0, 16
	v_add_lshl_u32 v1, v5, v11, 1
	v_lshl_add_u32 v154, v4, 11, v1
	v_lshl_add_u32 v156, v3, 11, v1
	v_ashrrev_i32_e32 v1, 31, v0
	v_lshrrev_b32_e32 v1, 22, v1
	v_add_u32_e32 v1, v0, v1
	v_ashrrev_i32_e32 v13, 10, v1
	v_mul_i32_i24_e32 v1, 0x400, v13
	v_sub_u32_e32 v0, v0, v1
	v_lshrrev_b32_e32 v1, 4, v0
	v_bitop3_b32 v0, v1, v0, 32 bitop3:0x6c
	v_ashrrev_i32_e32 v1, 31, v0
	s_ashr_i32 s1, s2, 2
	v_lshrrev_b32_e32 v1, 26, v1
	s_and_b32 s0, s2, 7
	s_and_b32 s1, s1, -8
	v_add_u32_e32 v1, v0, v1
	v_lshlrev_b32_e32 v3, 3, v13
	s_lshr_b32 s8, s93, 8
	s_or_b32 s0, s1, s0
	s_bfe_u32 s68, s2, 0x20003
	v_ashrrev_i32_e32 v14, 6, v1
	v_and_b32_e32 v3, -16, v3
	s_cmp_eq_u32 s8, 1
	v_add_u32_e32 v3, v14, v3
	s_cselect_b64 s[16:17], -1, 0
	s_ashr_i32 s1, s0, 31
	v_and_b32_e32 v4, 3, v14
	v_lshrrev_b32_e32 v5, 2, v3
	v_lshlrev_b32_e32 v6, 1, v3
	v_and_b32_e32 v1, 0xc0, v1
	s_lshl_b64 s[4:5], s[0:1], 19
	s_lshl_b32 s1, s68, 19
	v_and_or_b32 v4, v3, s11, v4
	v_and_b32_e32 v5, 4, v5
	v_and_b32_e32 v6, 24, v6
	v_sub_u32_e32 v0, v0, v1
	s_add_u32 s72, s64, s1
	v_or3_b32 v4, v4, v5, v6
	v_lshlrev_b32_e32 v5, 5, v13
	v_ashrrev_i16_sdwa v0, v2, sext(v0) dst_sel:DWORD dst_unused:UNUSED_PAD src0_sel:DWORD src1_sel:BYTE_0
	s_addc_u32 s73, s65, 0
	s_add_i32 s24, s3, 0
	v_and_b32_e32 v5, 32, v5
	v_bfe_i32 v15, v0, 0, 16
	s_add_i32 m0, s24, 0x10000
	s_add_i32 s1, s24, 0x12000
	v_add_lshl_u32 v0, v5, v15, 1
	s_add_u32 s6, s72, 0x40000
	v_lshl_add_u32 v152, v4, 11, v0
	s_addc_u32 s7, s73, 0
	s_add_i32 s9, s24, 0x14000
	s_add_i32 s10, s24, 0x16000
	global_load_lds_dwordx4 v152, s[72:73]
	s_mov_b32 m0, s1
	s_add_u32 s70, s48, s4
	global_load_lds_dwordx4 v154, s[72:73]
	s_mov_b32 m0, s9
	s_addc_u32 s71, s49, s5
	s_add_i32 s25, s24, 0x2000
	global_load_lds_dwordx4 v152, s[6:7]
	s_mov_b32 m0, s10
	s_add_u32 s4, s70, 0x40000
	v_lshl_add_u32 v158, v3, 11, v0
	global_load_lds_dwordx4 v154, s[6:7]
	s_mov_b32 m0, s24
	s_addc_u32 s5, s71, 0
	s_add_i32 s42, s24, 0x4000
	global_load_lds_dwordx4 v158, s[70:71]
	s_mov_b32 m0, s25
	s_add_i32 s43, s24, 0x6000
	global_load_lds_dwordx4 v156, s[70:71]
	s_mov_b32 m0, s42
	v_mov_b32_e32 v155, v153
	global_load_lds_dwordx4 v158, s[4:5]
	s_mov_b32 m0, s43
	v_mov_b32_e32 v159, v153
	global_load_lds_dwordx4 v156, s[4:5]
	v_mov_b32_e32 v157, v153
	s_mov_b32 s19, 0
	s_cmp_lg_u32 s8, 1
	v_lshl_add_u64 v[6:7], s[72:73], 0, v[152:153]
	v_lshl_add_u64 v[4:5], s[72:73], 0, v[154:155]
	v_lshl_add_u64 v[2:3], s[70:71], 0, v[158:159]
	v_lshl_add_u64 v[0:1], s[70:71], 0, v[156:157]
	s_cbranch_scc1 .LBB0_336
	s_barrier

.LBB0_495:
	s_cmp_lt_i32 s40, 8
	s_cselect_b64 s[14:15], -1, 0
	s_add_u32 s16, s54, 0x40000
	s_addc_u32 s17, s55, 0
	s_add_u32 s0, s54, 0xd800000
	s_addc_u32 s1, s55, 0
	s_add_u32 s20, s54, 0x1b00000
	s_addc_u32 s21, s55, 0
	s_add_u32 s26, s54, 0x1f00000
	s_addc_u32 s27, s55, 0
	s_add_u32 s36, s54, 0x3100000
	s_addc_u32 s37, s55, 0
	s_add_u32 s12, s54, 0x3200000
	s_addc_u32 s13, s55, 0
	v_writelane_b32 v246, s0, 10
	s_add_u32 s18, s54, 0x3a00000
	s_addc_u32 s19, s55, 0
	v_writelane_b32 v246, s1, 11
	s_and_b64 s[0:1], s[4:5], s[14:15]
	s_andn2_b64 vcc, exec, s[0:1]
	s_cbranch_vccnz .LBB0_572
	v_mov_b32_e32 v153, 0
	s_cmpk_gt_i32 s2, 0xbf
	v_mbcnt_lo_u32_b32 v8, -1, 0
	v_mbcnt_hi_u32_b32 v8, -1, v8
	s_waitcnt vmcnt(0)
	v_readlane_b32 s9, v247, 17
	v_readlane_b32 s10, v247, 16
	s_cbranch_scc1 .LBB0_541
	s_lshl_b32 s3, s94, 10
	v_lshlrev_b32_e32 v12, 4, v8
	v_add_u32_e32 v0, s3, v12
	v_add_u32_e32 v1, 0x2000, v0
	v_ashrrev_i32_e32 v2, 31, v1
	v_lshrrev_b32_e32 v2, 22, v2
	v_add_u32_e32 v2, v1, v2
	v_ashrrev_i32_e32 v9, 10, v2
	v_mul_i32_i24_e32 v2, 0x400, v9
	v_sub_u32_e32 v1, v1, v2
	v_lshrrev_b32_e32 v2, 4, v1
	v_bitop3_b32 v1, v2, v1, 32 bitop3:0x6c
	v_ashrrev_i32_e32 v2, 31, v1
	v_lshrrev_b32_e32 v2, 26, v2
	v_add_u32_e32 v2, v1, v2
	v_ashrrev_i32_e32 v10, 6, v2
	v_lshlrev_b32_e32 v3, 3, v9
	v_and_b32_e32 v2, 0xffc0, v2
	v_and_b32_e32 v3, -16, v3
	v_sub_u32_e32 v1, v1, v2
	v_add_u32_e32 v3, v10, v3
	v_lshrrev_b16_e32 v2, 7, v1
	v_and_b32_e32 v4, 3, v10
	s_mov_b32 s25, 0x7ffe0
	v_lshrrev_b32_e32 v5, 2, v3
	v_lshlrev_b32_e32 v6, 1, v3
	v_and_b32_e32 v2, 1, v2
	v_and_or_b32 v4, v3, s25, v4
	v_and_b32_e32 v5, 4, v5
	v_and_b32_e32 v6, 24, v6
	v_add_u16_e32 v1, v1, v2
	v_mov_b32_e32 v2, 1
	v_or3_b32 v4, v4, v5, v6
	v_lshlrev_b32_e32 v5, 5, v9
	v_ashrrev_i16_sdwa v1, v2, sext(v1) dst_sel:DWORD dst_unused:UNUSED_PAD src0_sel:DWORD src1_sel:BYTE_0
	v_and_b32_e32 v5, 32, v5
	v_bfe_i32 v11, v1, 0, 16
	v_add_lshl_u32 v1, v5, v11, 1
	v_lshl_add_u32 v154, v4, 13, v1
	v_lshl_add_u32 v156, v3, 13, v1
	v_ashrrev_i32_e32 v1, 31, v0
	v_lshrrev_b32_e32 v1, 22, v1
	v_add_u32_e32 v1, v0, v1
	v_ashrrev_i32_e32 v13, 10, v1
	v_mul_i32_i24_e32 v1, 0x400, v13
	v_sub_u32_e32 v0, v0, v1
	v_lshrrev_b32_e32 v1, 4, v0
	v_bitop3_b32 v0, v1, v0, 32 bitop3:0x6c
	v_ashrrev_i32_e32 v1, 31, v0
	s_ashr_i32 s1, s2, 2
	v_lshrrev_b32_e32 v1, 26, v1
	s_and_b32 s0, s2, 7
	s_and_b32 s1, s1, -8
	v_add_u32_e32 v1, v0, v1
	v_lshlrev_b32_e32 v3, 3, v13
	s_lshr_b32 s8, s93, 8
	s_or_b32 s0, s1, s0
	s_bfe_u32 s78, s2, 0x20003
	v_ashrrev_i32_e32 v14, 6, v1
	v_and_b32_e32 v3, -16, v3
	s_cmp_eq_u32 s8, 1
	v_add_u32_e32 v3, v14, v3
	s_cselect_b64 s[22:23], -1, 0
	s_ashr_i32 s1, s0, 31
	v_and_b32_e32 v4, 3, v14
	v_lshrrev_b32_e32 v5, 2, v3
	v_lshlrev_b32_e32 v6, 1, v3
	v_and_b32_e32 v1, 0xc0, v1
	s_lshl_b64 s[4:5], s[0:1], 21
	s_lshl_b32 s1, s78, 21
	v_and_or_b32 v4, v3, s25, v4
	v_and_b32_e32 v5, 4, v5
	v_and_b32_e32 v6, 24, v6
	v_sub_u32_e32 v0, v0, v1
	s_add_u32 s82, s50, s1
	v_or3_b32 v4, v4, v5, v6
	v_lshlrev_b32_e32 v5, 5, v13
	v_ashrrev_i16_sdwa v0, v2, sext(v0) dst_sel:DWORD dst_unused:UNUSED_PAD src0_sel:DWORD src1_sel:BYTE_0
	s_addc_u32 s83, s51, 0
	s_add_i32 s86, s3, 0
	v_and_b32_e32 v5, 32, v5
	v_bfe_i32 v15, v0, 0, 16
	s_add_i32 m0, s86, 0x10000
	s_add_i32 s1, s86, 0x12000
	v_add_lshl_u32 v0, v5, v15, 1
	s_add_u32 s6, s82, 0x100000
	v_lshl_add_u32 v152, v4, 13, v0
	s_addc_u32 s7, s83, 0
	s_add_i32 s11, s86, 0x14000
	s_add_i32 s24, s86, 0x16000
	global_load_lds_dwordx4 v152, s[82:83]
	s_mov_b32 m0, s1
	s_add_u32 s80, s44, s4
	global_load_lds_dwordx4 v154, s[82:83]
	s_mov_b32 m0, s11
	s_addc_u32 s81, s45, s5
	s_add_i32 s87, s86, 0x2000
	global_load_lds_dwordx4 v152, s[6:7]
	s_mov_b32 m0, s24
	s_add_u32 s4, s80, 0x100000
	v_lshl_add_u32 v158, v3, 13, v0
	global_load_lds_dwordx4 v154, s[6:7]
	s_mov_b32 m0, s86
	s_addc_u32 s5, s81, 0
	s_add_i32 s88, s86, 0x4000
	global_load_lds_dwordx4 v158, s[80:81]
	s_mov_b32 m0, s87
	s_add_i32 s89, s86, 0x6000
	global_load_lds_dwordx4 v156, s[80:81]
	s_mov_b32 m0, s88
	v_writelane_b32 v246, s96, 12
	global_load_lds_dwordx4 v158, s[4:5]
	s_mov_b32 m0, s89
	v_mov_b32_e32 v155, v153
	global_load_lds_dwordx4 v156, s[4:5]
	v_mov_b32_e32 v159, v153
	v_mov_b32_e32 v157, v153
	v_writelane_b32 v246, s97, 13
	s_mov_b32 s29, 0
	s_cmp_lg_u32 s8, 1
	v_lshl_add_u64 v[6:7], s[82:83], 0, v[152:153]
	v_lshl_add_u64 v[4:5], s[82:83], 0, v[154:155]
	v_lshl_add_u64 v[2:3], s[80:81], 0, v[158:159]
	v_lshl_add_u64 v[0:1], s[80:81], 0, v[156:157]
	v_writelane_b32 v246, s94, 14
	s_cbranch_scc1 .LBB0_499
	s_barrier

.LBB0_541:
	s_cmpk_lt_i32 s2, 0xc0
	s_cbranch_scc1 .LBB0_572
	v_mov_b32_e32 v1, 0
	s_add_i32 s3, s2, 0xffffff40
	s_lshl_b32 s0, s3, 3
	s_add_i32 s10, s94, s0
	v_readlane_b32 s28, v246, 8
	s_cmpk_gt_i32 s10, 0x67f
	v_readlane_b32 s29, v246, 9
	v_mbcnt_lo_u32_b32 v14, -1, 0
	v_mbcnt_hi_u32_b32 v14, -1, v14
	s_waitcnt vmcnt(2)
	v_readlane_b32 s5, v247, 39
	v_readlane_b32 s4, v247, 38
	s_waitcnt vmcnt(1)
	v_readlane_b32 s7, v247, 63
	v_readlane_b32 s6, v247, 62
	s_waitcnt vmcnt(0)
	v_readlane_b32 s9, v247, 59
	v_readlane_b32 s8, v247, 58
	s_cbranch_scc1 .LBB0_553
	v_lshlrev_b32_e32 v0, 2, v14
	v_and_b32_e32 v0, 0x7c, v0
	s_lshl_b32 s0, s94, 14
	v_ashrrev_i32_e32 v15, 5, v14
	v_lshl_add_u64 v[2:3], s[8:9], 0, v[0:1]
	s_movk_i32 s8, 0x84
	s_add_i32 s0, s0, 0
	v_mul_lo_u32 v4, v15, s8
	v_add3_u32 v16, s0, v0, v4
	v_lshlrev_b32_e32 v4, 3, v14
	v_ashrrev_i32_e32 v17, 3, v14
	v_and_b32_e32 v4, 56, v4
	v_mul_u32_u24_e32 v6, 0x84, v4
	v_lshlrev_b32_e32 v7, 2, v17
	v_lshlrev_b32_e32 v12, 1, v4
	v_mov_b32_e32 v13, v1
	v_add3_u32 v18, s0, v6, v7
	s_lshl_b32 s0, s10, 1
	s_mov_b32 s1, 0
	v_lshl_add_u64 v[4:5], s[36:37], 0, v[12:13]
	v_add_u32_e32 v19, 8, v17
	v_add_u32_e32 v20, 16, v17
	v_add_u32_e32 v21, 24, v17
	v_lshl_add_u64 v[6:7], s[6:7], 0, v[0:1]
	v_lshl_add_u64 v[8:9], s[26:27], 0, v[12:13]
	v_lshl_add_u64 v[10:11], s[4:5], 0, v[0:1]
	v_lshl_add_u64 v[12:13], s[20:21], 0, v[12:13]
	s_lshl_b32 s8, s10, 5
	s_lshl_b32 s9, s10, 2
	s_add_i32 s11, s0, 0x1f800
	v_add_u32_e32 v0, 0x400, v16
	v_add_u32_e32 v22, 0x800, v16
	v_add_u32_e32 v23, 0xc00, v16
	v_add_u32_e32 v24, 0x1000, v16
	v_add_u32_e32 v25, 0x1400, v16
	v_add_u32_e32 v26, 0x1800, v16
	v_add_u32_e32 v27, 0x1c00, v16
	s_branch .LBB0_545

.LBB0_553:
	s_lshl_b32 s0, s3, 9
	s_and_b32 s3, s93, 0xffffffc0
	s_add_i32 s0, s3, s0
	s_mov_b32 s4, 0x100000
	v_add_u32_e32 v0, s0, v14
	v_cmp_gt_i32_e32 vcc, s4, v0
	s_waitcnt vmcnt(2)
	v_readlane_b32 s7, v247, 53
	v_readlane_b32 s6, v247, 52
	s_waitcnt vmcnt(1)
	v_readlane_b32 s9, v247, 55
	v_readlane_b32 s8, v247, 54
	s_waitcnt vmcnt(0)
	v_readlane_b32 s1, v247, 57
	v_readlane_b32 s0, v247, 56
	s_and_saveexec_b64 s[4:5], vcc
	s_cbranch_execz .LBB0_566
	s_add_u32 s10, s54, 0x100000
	s_addc_u32 s11, s55, 0
	s_lshl_b32 s22, s2, 9
	s_add_i32 s22, s3, s22
	v_add_u32_e32 v1, s22, v14
	v_add_u32_e32 v1, 0xfffe0000, v1
	v_lshlrev_b32_e32 v10, 1, v0
	s_mov_b64 s[22:23], 0
	s_movk_i32 s24, 0x80
	v_mov_b32_e32 v3, 0
	s_mov_b32 s25, 0xf7fff
	v_mov_b32_e32 v4, v10
	v_mov_b32_e32 v5, v1

.LBB0_566:
	s_or_b64 exec, exec, s[4:5]
	v_mov_b32_e32 v1, 0
	s_mov_b32 s4, 0x40000
	v_cmp_gt_i32_e32 vcc, s4, v0
	s_waitcnt vmcnt(1)
	v_readlane_b32 s7, v247, 7
	v_readlane_b32 s6, v247, 6
	s_waitcnt vmcnt(0)
	v_readlane_b32 s1, v247, 9
	v_readlane_b32 s0, v247, 8
	s_and_saveexec_b64 s[4:5], vcc
	s_cbranch_execz .LBB0_571
	s_lshl_b32 s8, s2, 9
	s_add_i32 s3, s3, s8
	v_add_u32_e32 v1, s3, v14
	v_add_u32_e32 v8, 0xfffe0000, v1
	v_ashrrev_i32_e32 v1, 31, v0
	v_lshl_add_u64 v[2:3], v[0:1], 2, s[54:55]
	s_mov_b64 s[8:9], 0x300000
	v_lshl_add_u64 v[2:3], v[2:3], 0, s[8:9]
	v_lshl_add_u64 v[0:1], v[0:1], 3, s[6:7]
	s_mov_b64 s[6:7], 0
	s_mov_b64 s[8:9], 0x20000
	s_mov_b64 s[10:11], 0x40000
	s_mov_b32 s3, 0x37fff
	v_mov_b32_e32 v4, v8

.LBB0_820:
	v_mov_b32_e32 v5, 0
	s_lshl_b32 s0, s2, 3
	s_add_i32 s0, s94, s0
	s_add_i32 s3, s0, 0xfffffc00
	s_cmpk_gt_i32 s3, 0xfff
	s_waitcnt vmcnt(0)
	v_readlane_b32 s5, v247, 25
	v_readlane_b32 s4, v247, 24
	v_readlane_b32 s7, v247, 27
	v_readlane_b32 s6, v247, 26
	v_mbcnt_lo_u32_b32 v2, -1, 0
	v_mbcnt_hi_u32_b32 v2, -1, v2
	s_cbranch_scc1 .LBB0_827
	s_lshl_b32 s0, s94, 14
	v_ashrrev_i32_e32 v8, 5, v2
	v_lshlrev_b32_e32 v0, 2, v2
	v_ashrrev_i32_e32 v9, 3, v2
	v_lshlrev_b32_e32 v2, 3, v2
	s_add_i32 s0, s0, 0
	v_and_b32_e32 v4, 0x7c, v0
	s_movk_i32 s8, 0x84
	v_and_b32_e32 v2, 56, v2
	v_add_u32_e32 v14, s0, v4
	v_mul_lo_u32 v15, v8, s8
	v_mul_u32_u24_e32 v10, 0x84, v2
	v_lshlrev_b32_e32 v11, 2, v9
	v_lshl_add_u64 v[0:1], s[6:7], 0, v[4:5]
	s_mov_b64 s[6:7], 0x1000000
	v_lshlrev_b32_e32 v6, 1, v2
	v_mov_b32_e32 v7, v5
	v_add3_u32 v10, s0, v10, v11
	v_lshl_add_u64 v[4:5], s[4:5], 0, v[4:5]
	s_lshl_b32 s0, s3, 1
	v_add_u32_e32 v14, v14, v15
	s_mov_b32 s1, 0
	v_lshl_add_u64 v[0:1], v[0:1], 0, s[6:7]
	v_lshl_add_u64 v[2:3], s[28:29], 0, v[6:7]
	v_add_u32_e32 v11, 8, v9
	v_add_u32_e32 v12, 16, v9
	v_add_u32_e32 v13, 24, v9
	v_lshl_add_u64 v[4:5], v[4:5], 0, s[6:7]
	v_lshl_add_u64 v[6:7], s[30:31], 0, v[6:7]
	s_lshl_b32 s8, s3, 5
	s_add_i32 s9, s0, 0x1f000
	s_mov_b32 s20, 0x8000
	s_mov_b32 s21, 0x10000
	s_mov_b32 s22, 0x18000
	s_mov_b32 s23, 0x20000
	s_mov_b32 s24, 0x28000
	s_mov_b32 s25, 0x30000
	s_mov_b32 s33, 0x38000
	s_mov_b32 s34, 0x40000
	s_mov_b32 s35, 0x48000
	s_mov_b32 s42, 0x50000
	s_mov_b32 s43, 0x58000
	s_mov_b32 s60, 0x60000
	s_mov_b32 s61, 0x68000
	s_mov_b32 s62, 0x70000
	s_mov_b32 s63, 0x78000
	s_mov_b32 s64, 0x80000
	s_mov_b32 s65, 0x88000
	s_mov_b32 s66, 0x90000
	s_mov_b32 s67, 0x98000
	s_mov_b32 s68, 0xa0000
	s_mov_b32 s69, 0xa8000
	s_mov_b32 s70, 0xb0000
	s_mov_b32 s71, 0xb8000
	s_mov_b32 s72, 0xc0000
	s_mov_b32 s73, 0xc8000
	s_mov_b32 s74, 0xd0000
	s_mov_b32 s75, 0xd8000
	s_mov_b32 s76, 0xe0000
	s_mov_b32 s77, 0xe8000
	s_mov_b32 s78, 0xf0000
	s_mov_b32 s79, 0xf8000
	v_add_u32_e32 v15, 0x400, v14
	v_add_u32_e32 v16, 0x800, v14
	v_add_u32_e32 v17, 0xc00, v14
	v_add_u32_e32 v18, 0x1000, v14
	v_add_u32_e32 v19, 0x1400, v14
	v_add_u32_e32 v20, 0x1800, v14
	v_add_u32_e32 v21, 0x1c00, v14
	s_branch .LBB0_823

.LBB0_893:
	s_waitcnt vmcnt(0)
	v_cndmask_b32_e64 v0, 0, 1, s[0:1]
	v_cmp_ne_u32_e64 s[6:7], 1, v0
	s_andn2_b64 vcc, exec, s[0:1]
	s_waitcnt vmcnt(0) lgkmcnt(0)
	s_barrier
	s_cbranch_vccnz .LBB0_910
	v_mov_b32_e32 v3, 0
	v_mbcnt_lo_u32_b32 v0, -1, 0
	v_mbcnt_hi_u32_b32 v0, -1, v0
	v_lshlrev_b32_e32 v1, 3, v0
	v_lshlrev_b32_e32 v2, 2, v0
	s_movk_i32 s42, 0x200
	s_mul_i32 s16, s20, 3
	s_sub_i32 s35, s2, s16
	s_and_b32 s25, s94, 1
	s_lshr_b32 s21, s94, 1
	s_lshl_b32 s16, s25, 5
	s_add_i32 s16, s16, s20
	s_mul_i32 s16, s16, 17
	s_add_i32 s16, s16, 16
	s_lshl_b32 s16, s16, 9
	s_add_u32 s74, s54, 0x40000
	s_addc_u32 s75, s55, 0
	s_add_u32 s74, s74, s16
	s_addc_u32 s75, s75, 0
	global_load_dwordx2 v[4:5], v1, s[74:75]
	s_mov_b32 s10, 0xfffffc00
	s_cmp_eq_u32 s25, 0
	s_cselect_b32 s10, 0x400, s10
	s_cselect_b32 s11, 0, -1
	s_waitcnt vmcnt(1)
	v_readlane_b32 s70, v247, 10
	v_readlane_b32 s71, v247, 11
	v_readlane_b32 s72, v247, 12
	v_readlane_b32 s73, v247, 13
	s_cmp_eq_u32 s35, 0
	s_cbranch_scc1 .Lscan_ctx
	s_cmp_gt_u32 s94, 3
	s_cbranch_scc1 .Lscan_end
	s_lshl_b32 s16, s35, 1
	s_add_i32 s16, s16, s21
	s_sub_i32 s16, s16, 2
	s_lshl_b32 s19, s16, 7
	s_add_i32 s19, s19, 0x100
	s_mul_i32 s17, s20, 0x300
	s_add_i32 s17, s17, s19
	s_mul_i32 s18, s25, 127
	s_add_i32 s17, s17, s18
	s_lshl_b32 s17, s17, 10
	s_lshl_b32 s18, s25, 9
	s_add_u32 s0, s54, 0x4200000
	s_addc_u32 s1, s55, 0
	s_add_u32 s0, s0, s17
	s_addc_u32 s1, s1, 0
	s_add_u32 s0, s0, s18
	s_addc_u32 s1, s1, 0
	s_lshl_b32 s18, s25, 8
	s_add_u32 s8, s54, 0xa200000
	s_addc_u32 s9, s55, 0
	s_add_u32 s8, s8, s17
	s_addc_u32 s9, s9, 0
	s_add_u32 s8, s8, s18
	s_addc_u32 s9, s9, 0
	s_add_u32 s8, s8, 0x200
	s_addc_u32 s9, s9, 0
	global_load_dwordx2 v[32:33], v1, s[0:1]
	s_add_u32 s0, s0, s10
	s_addc_u32 s1, s1, s11
	global_load_dwordx2 v[34:35], v1, s[0:1]
	s_add_u32 s0, s0, s10
	s_addc_u32 s1, s1, s11
	global_load_dwordx2 v[36:37], v1, s[0:1]
	s_add_u32 s0, s0, s10
	s_addc_u32 s1, s1, s11
	global_load_dwordx2 v[38:39], v1, s[0:1]
	s_add_u32 s0, s0, s10
	s_addc_u32 s1, s1, s11
	global_load_dwordx2 v[40:41], v1, s[0:1]
	s_add_u32 s0, s0, s10
	s_addc_u32 s1, s1, s11
	global_load_dwordx2 v[42:43], v1, s[0:1]
	s_add_u32 s0, s0, s10
	s_addc_u32 s1, s1, s11
	global_load_dwordx2 v[44:45], v1, s[0:1]
	s_add_u32 s0, s0, s10
	s_addc_u32 s1, s1, s11
	global_load_dwordx2 v[46:47], v1, s[0:1]
	s_add_u32 s0, s0, s10
	s_addc_u32 s1, s1, s11
	global_load_dwordx2 v[48:49], v1, s[0:1]
	s_add_u32 s0, s0, s10
	s_addc_u32 s1, s1, s11
	global_load_dwordx2 v[50:51], v1, s[0:1]
	s_add_u32 s0, s0, s10
	s_addc_u32 s1, s1, s11
	global_load_dwordx2 v[52:53], v1, s[0:1]
	s_add_u32 s0, s0, s10
	s_addc_u32 s1, s1, s11
	global_load_dwordx2 v[54:55], v1, s[0:1]
	s_add_u32 s0, s0, s10
	s_addc_u32 s1, s1, s11
	global_load_dwordx2 v[56:57], v1, s[0:1]
	s_add_u32 s0, s0, s10
	s_addc_u32 s1, s1, s11
	global_load_dwordx2 v[58:59], v1, s[0:1]
	s_add_u32 s0, s0, s10
	s_addc_u32 s1, s1, s11
	global_load_dwordx2 v[60:61], v1, s[0:1]
	s_add_u32 s0, s0, s10
	s_addc_u32 s1, s1, s11
	global_load_dwordx2 v[62:63], v1, s[0:1]
	s_add_u32 s0, s0, s10
	s_addc_u32 s1, s1, s11
	global_load_dwordx2 v[64:65], v1, s[0:1]
	s_add_u32 s0, s0, s10
	s_addc_u32 s1, s1, s11
	global_load_dwordx2 v[66:67], v1, s[0:1]
	s_add_u32 s0, s0, s10
	s_addc_u32 s1, s1, s11
	global_load_dwordx2 v[68:69], v1, s[0:1]
	s_add_u32 s0, s0, s10
	s_addc_u32 s1, s1, s11
	global_load_dwordx2 v[70:71], v1, s[0:1]
	s_add_u32 s0, s0, s10
	s_addc_u32 s1, s1, s11
	global_load_dwordx2 v[72:73], v1, s[0:1]
	s_add_u32 s0, s0, s10
	s_addc_u32 s1, s1, s11
	global_load_dwordx2 v[74:75], v1, s[0:1]
	s_add_u32 s0, s0, s10
	s_addc_u32 s1, s1, s11
	global_load_dwordx2 v[76:77], v1, s[0:1]
	s_add_u32 s0, s0, s10
	s_addc_u32 s1, s1, s11
	global_load_dwordx2 v[78:79], v1, s[0:1]
	s_add_u32 s0, s0, s10
	s_addc_u32 s1, s1, s11
	global_load_dwordx2 v[80:81], v1, s[0:1]
	s_add_u32 s0, s0, s10
	s_addc_u32 s1, s1, s11
	global_load_dwordx2 v[82:83], v1, s[0:1]
	s_add_u32 s0, s0, s10
	s_addc_u32 s1, s1, s11
	global_load_dwordx2 v[84:85], v1, s[0:1]
	s_add_u32 s0, s0, s10
	s_addc_u32 s1, s1, s11
	global_load_dwordx2 v[86:87], v1, s[0:1]
	s_add_u32 s0, s0, s10
	s_addc_u32 s1, s1, s11
	global_load_dwordx2 v[88:89], v1, s[0:1]
	s_add_u32 s0, s0, s10
	s_addc_u32 s1, s1, s11
	global_load_dwordx2 v[90:91], v1, s[0:1]
	s_add_u32 s0, s0, s10
	s_addc_u32 s1, s1, s11
	global_load_dwordx2 v[92:93], v1, s[0:1]
	s_add_u32 s0, s0, s10
	s_addc_u32 s1, s1, s11
	global_load_dwordx2 v[94:95], v1, s[0:1]
	s_add_u32 s0, s0, s10
	s_addc_u32 s1, s1, s11
	s_lshl_b32 s17, s16, 1
	s_add_i32 s17, s17, s25
	s_lshl_b32 s17, s17, 5
	s_add_i32 s17, s17, s20
	s_lshl_b32 s17, s17, 8
	s_add_u32 s70, s70, s17
	s_addc_u32 s71, s71, 0
	s_add_u32 s72, s72, s17
	s_addc_u32 s73, s73, 0
	global_load_dword v6, v2, s[70:71]
	global_load_dword v7, v2, s[72:73]
	s_waitcnt vmcnt(18)
	s_waitcnt vmcnt(0)
	v_cvt_pk_bf16_f32 v8, v6, v7
	global_store_dword v2, v8, s[8:9]
	s_add_u32 s8, s8, s10
	s_addc_u32 s9, s9, s11
	v_mul_f32_e32 v9, v5, v7
	v_mul_f32_e32 v10, v5, v6
	v_fma_f32 v9, v4, v6, -v9
	v_fma_f32 v10, v4, v7, v10
	v_add_f32_e32 v6, v9, v32
	v_add_f32_e32 v7, v10, v33
	v_cvt_pk_bf16_f32 v8, v6, v7
	global_store_dword v2, v8, s[8:9]
	s_add_u32 s8, s8, s10
	s_addc_u32 s9, s9, s11
	v_mul_f32_e32 v9, v5, v7
	v_mul_f32_e32 v10, v5, v6
	v_fma_f32 v9, v4, v6, -v9
	v_fma_f32 v10, v4, v7, v10
	v_add_f32_e32 v6, v9, v34
	v_add_f32_e32 v7, v10, v35
	v_cvt_pk_bf16_f32 v8, v6, v7
	global_store_dword v2, v8, s[8:9]
	s_add_u32 s8, s8, s10
	s_addc_u32 s9, s9, s11
	v_mul_f32_e32 v9, v5, v7
	v_mul_f32_e32 v10, v5, v6
	v_fma_f32 v9, v4, v6, -v9
	v_fma_f32 v10, v4, v7, v10
	v_add_f32_e32 v6, v9, v36
	v_add_f32_e32 v7, v10, v37
	v_cvt_pk_bf16_f32 v8, v6, v7
	global_store_dword v2, v8, s[8:9]
	s_add_u32 s8, s8, s10
	s_addc_u32 s9, s9, s11
	v_mul_f32_e32 v9, v5, v7
	v_mul_f32_e32 v10, v5, v6
	v_fma_f32 v9, v4, v6, -v9
	v_fma_f32 v10, v4, v7, v10
	v_add_f32_e32 v6, v9, v38
	v_add_f32_e32 v7, v10, v39
	v_cvt_pk_bf16_f32 v8, v6, v7
	global_store_dword v2, v8, s[8:9]
	s_add_u32 s8, s8, s10
	s_addc_u32 s9, s9, s11
	v_mul_f32_e32 v9, v5, v7
	v_mul_f32_e32 v10, v5, v6
	v_fma_f32 v9, v4, v6, -v9
	v_fma_f32 v10, v4, v7, v10
	v_add_f32_e32 v6, v9, v40
	v_add_f32_e32 v7, v10, v41
	v_cvt_pk_bf16_f32 v8, v6, v7
	global_store_dword v2, v8, s[8:9]
	s_add_u32 s8, s8, s10
	s_addc_u32 s9, s9, s11
	v_mul_f32_e32 v9, v5, v7
	v_mul_f32_e32 v10, v5, v6
	v_fma_f32 v9, v4, v6, -v9
	v_fma_f32 v10, v4, v7, v10
	v_add_f32_e32 v6, v9, v42
	v_add_f32_e32 v7, v10, v43
	v_cvt_pk_bf16_f32 v8, v6, v7
	global_store_dword v2, v8, s[8:9]
	s_add_u32 s8, s8, s10
	s_addc_u32 s9, s9, s11
	v_mul_f32_e32 v9, v5, v7
	v_mul_f32_e32 v10, v5, v6
	v_fma_f32 v9, v4, v6, -v9
	v_fma_f32 v10, v4, v7, v10
	v_add_f32_e32 v6, v9, v44
	v_add_f32_e32 v7, v10, v45
	v_cvt_pk_bf16_f32 v8, v6, v7
	global_store_dword v2, v8, s[8:9]
	s_add_u32 s8, s8, s10
	s_addc_u32 s9, s9, s11
	v_mul_f32_e32 v9, v5, v7
	v_mul_f32_e32 v10, v5, v6
	v_fma_f32 v9, v4, v6, -v9
	v_fma_f32 v10, v4, v7, v10
	v_add_f32_e32 v6, v9, v46
	v_add_f32_e32 v7, v10, v47
	v_cvt_pk_bf16_f32 v8, v6, v7
	global_store_dword v2, v8, s[8:9]
	s_add_u32 s8, s8, s10
	s_addc_u32 s9, s9, s11
	v_mul_f32_e32 v9, v5, v7
	v_mul_f32_e32 v10, v5, v6
	v_fma_f32 v9, v4, v6, -v9
	v_fma_f32 v10, v4, v7, v10
	v_add_f32_e32 v6, v9, v48
	v_add_f32_e32 v7, v10, v49
	v_cvt_pk_bf16_f32 v8, v6, v7
	global_store_dword v2, v8, s[8:9]
	s_add_u32 s8, s8, s10
	s_addc_u32 s9, s9, s11
	v_mul_f32_e32 v9, v5, v7
	v_mul_f32_e32 v10, v5, v6
	v_fma_f32 v9, v4, v6, -v9
	v_fma_f32 v10, v4, v7, v10
	v_add_f32_e32 v6, v9, v50
	v_add_f32_e32 v7, v10, v51
	v_cvt_pk_bf16_f32 v8, v6, v7
	global_store_dword v2, v8, s[8:9]
	s_add_u32 s8, s8, s10
	s_addc_u32 s9, s9, s11
	v_mul_f32_e32 v9, v5, v7
	v_mul_f32_e32 v10, v5, v6
	v_fma_f32 v9, v4, v6, -v9
	v_fma_f32 v10, v4, v7, v10
	v_add_f32_e32 v6, v9, v52
	v_add_f32_e32 v7, v10, v53
	v_cvt_pk_bf16_f32 v8, v6, v7
	global_store_dword v2, v8, s[8:9]
	s_add_u32 s8, s8, s10
	s_addc_u32 s9, s9, s11
	v_mul_f32_e32 v9, v5, v7
	v_mul_f32_e32 v10, v5, v6
	v_fma_f32 v9, v4, v6, -v9
	v_fma_f32 v10, v4, v7, v10
	v_add_f32_e32 v6, v9, v54
	v_add_f32_e32 v7, v10, v55
	v_cvt_pk_bf16_f32 v8, v6, v7
	global_store_dword v2, v8, s[8:9]
	s_add_u32 s8, s8, s10
	s_addc_u32 s9, s9, s11
	v_mul_f32_e32 v9, v5, v7
	v_mul_f32_e32 v10, v5, v6
	v_fma_f32 v9, v4, v6, -v9
	v_fma_f32 v10, v4, v7, v10
	v_add_f32_e32 v6, v9, v56
	v_add_f32_e32 v7, v10, v57
	v_cvt_pk_bf16_f32 v8, v6, v7
	global_store_dword v2, v8, s[8:9]
	s_add_u32 s8, s8, s10
	s_addc_u32 s9, s9, s11
	v_mul_f32_e32 v9, v5, v7
	v_mul_f32_e32 v10, v5, v6
	v_fma_f32 v9, v4, v6, -v9
	v_fma_f32 v10, v4, v7, v10
	v_add_f32_e32 v6, v9, v58
	v_add_f32_e32 v7, v10, v59
	v_cvt_pk_bf16_f32 v8, v6, v7
	global_store_dword v2, v8, s[8:9]
	s_add_u32 s8, s8, s10
	s_addc_u32 s9, s9, s11
	v_mul_f32_e32 v9, v5, v7
	v_mul_f32_e32 v10, v5, v6
	v_fma_f32 v9, v4, v6, -v9
	v_fma_f32 v10, v4, v7, v10
	v_add_f32_e32 v6, v9, v60
	v_add_f32_e32 v7, v10, v61
	v_cvt_pk_bf16_f32 v8, v6, v7
	global_store_dword v2, v8, s[8:9]
	s_add_u32 s8, s8, s10
	s_addc_u32 s9, s9, s11
	v_mul_f32_e32 v9, v5, v7
	v_mul_f32_e32 v10, v5, v6
	v_fma_f32 v9, v4, v6, -v9
	v_fma_f32 v10, v4, v7, v10
	v_add_f32_e32 v6, v9, v62
	v_add_f32_e32 v7, v10, v63
	global_load_dwordx2 v[96:97], v1, s[0:1]
	s_add_u32 s0, s0, s10
	s_addc_u32 s1, s1, s11
	global_load_dwordx2 v[98:99], v1, s[0:1]
	s_add_u32 s0, s0, s10
	s_addc_u32 s1, s1, s11
	global_load_dwordx2 v[100:101], v1, s[0:1]
	s_add_u32 s0, s0, s10
	s_addc_u32 s1, s1, s11
	global_load_dwordx2 v[102:103], v1, s[0:1]
	s_add_u32 s0, s0, s10
	s_addc_u32 s1, s1, s11
	global_load_dwordx2 v[104:105], v1, s[0:1]
	s_add_u32 s0, s0, s10
	s_addc_u32 s1, s1, s11
	global_load_dwordx2 v[106:107], v1, s[0:1]
	s_add_u32 s0, s0, s10
	s_addc_u32 s1, s1, s11
	global_load_dwordx2 v[108:109], v1, s[0:1]
	s_add_u32 s0, s0, s10
	s_addc_u32 s1, s1, s11
	global_load_dwordx2 v[110:111], v1, s[0:1]
	s_add_u32 s0, s0, s10
	s_addc_u32 s1, s1, s11
	global_load_dwordx2 v[112:113], v1, s[0:1]
	s_add_u32 s0, s0, s10
	s_addc_u32 s1, s1, s11
	global_load_dwordx2 v[114:115], v1, s[0:1]
	s_add_u32 s0, s0, s10
	s_addc_u32 s1, s1, s11
	global_load_dwordx2 v[116:117], v1, s[0:1]
	s_add_u32 s0, s0, s10
	s_addc_u32 s1, s1, s11
	global_load_dwordx2 v[118:119], v1, s[0:1]
	s_add_u32 s0, s0, s10
	s_addc_u32 s1, s1, s11
	global_load_dwordx2 v[120:121], v1, s[0:1]
	s_add_u32 s0, s0, s10
	s_addc_u32 s1, s1, s11
	global_load_dwordx2 v[122:123], v1, s[0:1]
	s_add_u32 s0, s0, s10
	s_addc_u32 s1, s1, s11
	global_load_dwordx2 v[124:125], v1, s[0:1]
	s_add_u32 s0, s0, s10
	s_addc_u32 s1, s1, s11
	global_load_dwordx2 v[126:127], v1, s[0:1]
	s_add_u32 s0, s0, s10
	s_addc_u32 s1, s1, s11
	s_waitcnt vmcnt(34)
	v_cvt_pk_bf16_f32 v8, v6, v7
	global_store_dword v2, v8, s[8:9]
	s_add_u32 s8, s8, s10
	s_addc_u32 s9, s9, s11
	v_mul_f32_e32 v9, v5, v7
	v_mul_f32_e32 v10, v5, v6
	v_fma_f32 v9, v4, v6, -v9
	v_fma_f32 v10, v4, v7, v10
	v_add_f32_e32 v6, v9, v64
	v_add_f32_e32 v7, v10, v65
	v_cvt_pk_bf16_f32 v8, v6, v7
	global_store_dword v2, v8, s[8:9]
	s_add_u32 s8, s8, s10
	s_addc_u32 s9, s9, s11
	v_mul_f32_e32 v9, v5, v7
	v_mul_f32_e32 v10, v5, v6
	v_fma_f32 v9, v4, v6, -v9
	v_fma_f32 v10, v4, v7, v10
	v_add_f32_e32 v6, v9, v66
	v_add_f32_e32 v7, v10, v67
	v_cvt_pk_bf16_f32 v8, v6, v7
	global_store_dword v2, v8, s[8:9]
	s_add_u32 s8, s8, s10
	s_addc_u32 s9, s9, s11
	v_mul_f32_e32 v9, v5, v7
	v_mul_f32_e32 v10, v5, v6
	v_fma_f32 v9, v4, v6, -v9
	v_fma_f32 v10, v4, v7, v10
	v_add_f32_e32 v6, v9, v68
	v_add_f32_e32 v7, v10, v69
	v_cvt_pk_bf16_f32 v8, v6, v7
	global_store_dword v2, v8, s[8:9]
	s_add_u32 s8, s8, s10
	s_addc_u32 s9, s9, s11
	v_mul_f32_e32 v9, v5, v7
	v_mul_f32_e32 v10, v5, v6
	v_fma_f32 v9, v4, v6, -v9
	v_fma_f32 v10, v4, v7, v10
	v_add_f32_e32 v6, v9, v70
	v_add_f32_e32 v7, v10, v71
	v_cvt_pk_bf16_f32 v8, v6, v7
	global_store_dword v2, v8, s[8:9]
	s_add_u32 s8, s8, s10
	s_addc_u32 s9, s9, s11
	v_mul_f32_e32 v9, v5, v7
	v_mul_f32_e32 v10, v5, v6
	v_fma_f32 v9, v4, v6, -v9
	v_fma_f32 v10, v4, v7, v10
	v_add_f32_e32 v6, v9, v72
	v_add_f32_e32 v7, v10, v73
	v_cvt_pk_bf16_f32 v8, v6, v7
	global_store_dword v2, v8, s[8:9]
	s_add_u32 s8, s8, s10
	s_addc_u32 s9, s9, s11
	v_mul_f32_e32 v9, v5, v7
	v_mul_f32_e32 v10, v5, v6
	v_fma_f32 v9, v4, v6, -v9
	v_fma_f32 v10, v4, v7, v10
	v_add_f32_e32 v6, v9, v74
	v_add_f32_e32 v7, v10, v75
	v_cvt_pk_bf16_f32 v8, v6, v7
	global_store_dword v2, v8, s[8:9]
	s_add_u32 s8, s8, s10
	s_addc_u32 s9, s9, s11
	v_mul_f32_e32 v9, v5, v7
	v_mul_f32_e32 v10, v5, v6
	v_fma_f32 v9, v4, v6, -v9
	v_fma_f32 v10, v4, v7, v10
	v_add_f32_e32 v6, v9, v76
	v_add_f32_e32 v7, v10, v77
	v_cvt_pk_bf16_f32 v8, v6, v7
	global_store_dword v2, v8, s[8:9]
	s_add_u32 s8, s8, s10
	s_addc_u32 s9, s9, s11
	v_mul_f32_e32 v9, v5, v7
	v_mul_f32_e32 v10, v5, v6
	v_fma_f32 v9, v4, v6, -v9
	v_fma_f32 v10, v4, v7, v10
	v_add_f32_e32 v6, v9, v78
	v_add_f32_e32 v7, v10, v79
	v_cvt_pk_bf16_f32 v8, v6, v7
	global_store_dword v2, v8, s[8:9]
	s_add_u32 s8, s8, s10
	s_addc_u32 s9, s9, s11
	v_mul_f32_e32 v9, v5, v7
	v_mul_f32_e32 v10, v5, v6
	v_fma_f32 v9, v4, v6, -v9
	v_fma_f32 v10, v4, v7, v10
	v_add_f32_e32 v6, v9, v80
	v_add_f32_e32 v7, v10, v81
	v_cvt_pk_bf16_f32 v8, v6, v7
	global_store_dword v2, v8, s[8:9]
	s_add_u32 s8, s8, s10
	s_addc_u32 s9, s9, s11
	v_mul_f32_e32 v9, v5, v7
	v_mul_f32_e32 v10, v5, v6
	v_fma_f32 v9, v4, v6, -v9
	v_fma_f32 v10, v4, v7, v10
	v_add_f32_e32 v6, v9, v82
	v_add_f32_e32 v7, v10, v83
	v_cvt_pk_bf16_f32 v8, v6, v7
	global_store_dword v2, v8, s[8:9]
	s_add_u32 s8, s8, s10
	s_addc_u32 s9, s9, s11
	v_mul_f32_e32 v9, v5, v7
	v_mul_f32_e32 v10, v5, v6
	v_fma_f32 v9, v4, v6, -v9
	v_fma_f32 v10, v4, v7, v10
	v_add_f32_e32 v6, v9, v84
	v_add_f32_e32 v7, v10, v85
	v_cvt_pk_bf16_f32 v8, v6, v7
	global_store_dword v2, v8, s[8:9]
	s_add_u32 s8, s8, s10
	s_addc_u32 s9, s9, s11
	v_mul_f32_e32 v9, v5, v7
	v_mul_f32_e32 v10, v5, v6
	v_fma_f32 v9, v4, v6, -v9
	v_fma_f32 v10, v4, v7, v10
	v_add_f32_e32 v6, v9, v86
	v_add_f32_e32 v7, v10, v87
	v_cvt_pk_bf16_f32 v8, v6, v7
	global_store_dword v2, v8, s[8:9]
	s_add_u32 s8, s8, s10
	s_addc_u32 s9, s9, s11
	v_mul_f32_e32 v9, v5, v7
	v_mul_f32_e32 v10, v5, v6
	v_fma_f32 v9, v4, v6, -v9
	v_fma_f32 v10, v4, v7, v10
	v_add_f32_e32 v6, v9, v88
	v_add_f32_e32 v7, v10, v89
	v_cvt_pk_bf16_f32 v8, v6, v7
	global_store_dword v2, v8, s[8:9]
	s_add_u32 s8, s8, s10
	s_addc_u32 s9, s9, s11
	v_mul_f32_e32 v9, v5, v7
	v_mul_f32_e32 v10, v5, v6
	v_fma_f32 v9, v4, v6, -v9
	v_fma_f32 v10, v4, v7, v10
	v_add_f32_e32 v6, v9, v90
	v_add_f32_e32 v7, v10, v91
	v_cvt_pk_bf16_f32 v8, v6, v7
	global_store_dword v2, v8, s[8:9]
	s_add_u32 s8, s8, s10
	s_addc_u32 s9, s9, s11
	v_mul_f32_e32 v9, v5, v7
	v_mul_f32_e32 v10, v5, v6
	v_fma_f32 v9, v4, v6, -v9
	v_fma_f32 v10, v4, v7, v10
	v_add_f32_e32 v6, v9, v92
	v_add_f32_e32 v7, v10, v93
	v_cvt_pk_bf16_f32 v8, v6, v7
	global_store_dword v2, v8, s[8:9]
	s_add_u32 s8, s8, s10
	s_addc_u32 s9, s9, s11
	v_mul_f32_e32 v9, v5, v7
	v_mul_f32_e32 v10, v5, v6
	v_fma_f32 v9, v4, v6, -v9
	v_fma_f32 v10, v4, v7, v10
	v_add_f32_e32 v6, v9, v94
	v_add_f32_e32 v7, v10, v95
	global_load_dwordx2 v[32:33], v1, s[0:1]
	s_add_u32 s0, s0, s10
	s_addc_u32 s1, s1, s11
	global_load_dwordx2 v[34:35], v1, s[0:1]
	s_add_u32 s0, s0, s10
	s_addc_u32 s1, s1, s11
	global_load_dwordx2 v[36:37], v1, s[0:1]
	s_add_u32 s0, s0, s10
	s_addc_u32 s1, s1, s11
	global_load_dwordx2 v[38:39], v1, s[0:1]
	s_add_u32 s0, s0, s10
	s_addc_u32 s1, s1, s11
	global_load_dwordx2 v[40:41], v1, s[0:1]
	s_add_u32 s0, s0, s10
	s_addc_u32 s1, s1, s11
	global_load_dwordx2 v[42:43], v1, s[0:1]
	s_add_u32 s0, s0, s10
	s_addc_u32 s1, s1, s11
	global_load_dwordx2 v[44:45], v1, s[0:1]
	s_add_u32 s0, s0, s10
	s_addc_u32 s1, s1, s11
	global_load_dwordx2 v[46:47], v1, s[0:1]
	s_add_u32 s0, s0, s10
	s_addc_u32 s1, s1, s11
	global_load_dwordx2 v[48:49], v1, s[0:1]
	s_add_u32 s0, s0, s10
	s_addc_u32 s1, s1, s11
	global_load_dwordx2 v[50:51], v1, s[0:1]
	s_add_u32 s0, s0, s10
	s_addc_u32 s1, s1, s11
	global_load_dwordx2 v[52:53], v1, s[0:1]
	s_add_u32 s0, s0, s10
	s_addc_u32 s1, s1, s11
	global_load_dwordx2 v[54:55], v1, s[0:1]
	s_add_u32 s0, s0, s10
	s_addc_u32 s1, s1, s11
	global_load_dwordx2 v[56:57], v1, s[0:1]
	s_add_u32 s0, s0, s10
	s_addc_u32 s1, s1, s11
	global_load_dwordx2 v[58:59], v1, s[0:1]
	s_add_u32 s0, s0, s10
	s_addc_u32 s1, s1, s11
	global_load_dwordx2 v[60:61], v1, s[0:1]
	s_add_u32 s0, s0, s10
	s_addc_u32 s1, s1, s11
	global_load_dwordx2 v[62:63], v1, s[0:1]
	s_add_u32 s0, s0, s10
	s_addc_u32 s1, s1, s11
	s_waitcnt vmcnt(32)
	v_cvt_pk_bf16_f32 v8, v6, v7
	global_store_dword v2, v8, s[8:9]
	s_add_u32 s8, s8, s10
	s_addc_u32 s9, s9, s11
	v_mul_f32_e32 v9, v5, v7
	v_mul_f32_e32 v10, v5, v6
	v_fma_f32 v9, v4, v6, -v9
	v_fma_f32 v10, v4, v7, v10
	v_add_f32_e32 v6, v9, v96
	v_add_f32_e32 v7, v10, v97
	v_cvt_pk_bf16_f32 v8, v6, v7
	global_store_dword v2, v8, s[8:9]
	s_add_u32 s8, s8, s10
	s_addc_u32 s9, s9, s11
	v_mul_f32_e32 v9, v5, v7
	v_mul_f32_e32 v10, v5, v6
	v_fma_f32 v9, v4, v6, -v9
	v_fma_f32 v10, v4, v7, v10
	v_add_f32_e32 v6, v9, v98
	v_add_f32_e32 v7, v10, v99
	v_cvt_pk_bf16_f32 v8, v6, v7
	global_store_dword v2, v8, s[8:9]
	s_add_u32 s8, s8, s10
	s_addc_u32 s9, s9, s11
	v_mul_f32_e32 v9, v5, v7
	v_mul_f32_e32 v10, v5, v6
	v_fma_f32 v9, v4, v6, -v9
	v_fma_f32 v10, v4, v7, v10
	v_add_f32_e32 v6, v9, v100
	v_add_f32_e32 v7, v10, v101
	v_cvt_pk_bf16_f32 v8, v6, v7
	global_store_dword v2, v8, s[8:9]
	s_add_u32 s8, s8, s10
	s_addc_u32 s9, s9, s11
	v_mul_f32_e32 v9, v5, v7
	v_mul_f32_e32 v10, v5, v6
	v_fma_f32 v9, v4, v6, -v9
	v_fma_f32 v10, v4, v7, v10
	v_add_f32_e32 v6, v9, v102
	v_add_f32_e32 v7, v10, v103
	v_cvt_pk_bf16_f32 v8, v6, v7
	global_store_dword v2, v8, s[8:9]
	s_add_u32 s8, s8, s10
	s_addc_u32 s9, s9, s11
	v_mul_f32_e32 v9, v5, v7
	v_mul_f32_e32 v10, v5, v6
	v_fma_f32 v9, v4, v6, -v9
	v_fma_f32 v10, v4, v7, v10
	v_add_f32_e32 v6, v9, v104
	v_add_f32_e32 v7, v10, v105
	v_cvt_pk_bf16_f32 v8, v6, v7
	global_store_dword v2, v8, s[8:9]
	s_add_u32 s8, s8, s10
	s_addc_u32 s9, s9, s11
	v_mul_f32_e32 v9, v5, v7
	v_mul_f32_e32 v10, v5, v6
	v_fma_f32 v9, v4, v6, -v9
	v_fma_f32 v10, v4, v7, v10
	v_add_f32_e32 v6, v9, v106
	v_add_f32_e32 v7, v10, v107
	v_cvt_pk_bf16_f32 v8, v6, v7
	global_store_dword v2, v8, s[8:9]
	s_add_u32 s8, s8, s10
	s_addc_u32 s9, s9, s11
	v_mul_f32_e32 v9, v5, v7
	v_mul_f32_e32 v10, v5, v6
	v_fma_f32 v9, v4, v6, -v9
	v_fma_f32 v10, v4, v7, v10
	v_add_f32_e32 v6, v9, v108
	v_add_f32_e32 v7, v10, v109
	v_cvt_pk_bf16_f32 v8, v6, v7
	global_store_dword v2, v8, s[8:9]
	s_add_u32 s8, s8, s10
	s_addc_u32 s9, s9, s11
	v_mul_f32_e32 v9, v5, v7
	v_mul_f32_e32 v10, v5, v6
	v_fma_f32 v9, v4, v6, -v9
	v_fma_f32 v10, v4, v7, v10
	v_add_f32_e32 v6, v9, v110
	v_add_f32_e32 v7, v10, v111
	v_cvt_pk_bf16_f32 v8, v6, v7
	global_store_dword v2, v8, s[8:9]
	s_add_u32 s8, s8, s10
	s_addc_u32 s9, s9, s11
	v_mul_f32_e32 v9, v5, v7
	v_mul_f32_e32 v10, v5, v6
	v_fma_f32 v9, v4, v6, -v9
	v_fma_f32 v10, v4, v7, v10
	v_add_f32_e32 v6, v9, v112
	v_add_f32_e32 v7, v10, v113
	v_cvt_pk_bf16_f32 v8, v6, v7
	global_store_dword v2, v8, s[8:9]
	s_add_u32 s8, s8, s10
	s_addc_u32 s9, s9, s11
	v_mul_f32_e32 v9, v5, v7
	v_mul_f32_e32 v10, v5, v6
	v_fma_f32 v9, v4, v6, -v9
	v_fma_f32 v10, v4, v7, v10
	v_add_f32_e32 v6, v9, v114
	v_add_f32_e32 v7, v10, v115
	v_cvt_pk_bf16_f32 v8, v6, v7
	global_store_dword v2, v8, s[8:9]
	s_add_u32 s8, s8, s10
	s_addc_u32 s9, s9, s11
	v_mul_f32_e32 v9, v5, v7
	v_mul_f32_e32 v10, v5, v6
	v_fma_f32 v9, v4, v6, -v9
	v_fma_f32 v10, v4, v7, v10
	v_add_f32_e32 v6, v9, v116
	v_add_f32_e32 v7, v10, v117
	v_cvt_pk_bf16_f32 v8, v6, v7
	global_store_dword v2, v8, s[8:9]
	s_add_u32 s8, s8, s10
	s_addc_u32 s9, s9, s11
	v_mul_f32_e32 v9, v5, v7
	v_mul_f32_e32 v10, v5, v6
	v_fma_f32 v9, v4, v6, -v9
	v_fma_f32 v10, v4, v7, v10
	v_add_f32_e32 v6, v9, v118
	v_add_f32_e32 v7, v10, v119
	v_cvt_pk_bf16_f32 v8, v6, v7
	global_store_dword v2, v8, s[8:9]
	s_add_u32 s8, s8, s10
	s_addc_u32 s9, s9, s11
	v_mul_f32_e32 v9, v5, v7
	v_mul_f32_e32 v10, v5, v6
	v_fma_f32 v9, v4, v6, -v9
	v_fma_f32 v10, v4, v7, v10
	v_add_f32_e32 v6, v9, v120
	v_add_f32_e32 v7, v10, v121
	v_cvt_pk_bf16_f32 v8, v6, v7
	global_store_dword v2, v8, s[8:9]
	s_add_u32 s8, s8, s10
	s_addc_u32 s9, s9, s11
	v_mul_f32_e32 v9, v5, v7
	v_mul_f32_e32 v10, v5, v6
	v_fma_f32 v9, v4, v6, -v9
	v_fma_f32 v10, v4, v7, v10
	v_add_f32_e32 v6, v9, v122
	v_add_f32_e32 v7, v10, v123
	v_cvt_pk_bf16_f32 v8, v6, v7
	global_store_dword v2, v8, s[8:9]
	s_add_u32 s8, s8, s10
	s_addc_u32 s9, s9, s11
	v_mul_f32_e32 v9, v5, v7
	v_mul_f32_e32 v10, v5, v6
	v_fma_f32 v9, v4, v6, -v9
	v_fma_f32 v10, v4, v7, v10
	v_add_f32_e32 v6, v9, v124
	v_add_f32_e32 v7, v10, v125
	v_cvt_pk_bf16_f32 v8, v6, v7
	global_store_dword v2, v8, s[8:9]
	s_add_u32 s8, s8, s10
	s_addc_u32 s9, s9, s11
	v_mul_f32_e32 v9, v5, v7
	v_mul_f32_e32 v10, v5, v6
	v_fma_f32 v9, v4, v6, -v9
	v_fma_f32 v10, v4, v7, v10
	v_add_f32_e32 v6, v9, v126
	v_add_f32_e32 v7, v10, v127
	global_load_dwordx2 v[64:65], v1, s[0:1]
	s_add_u32 s0, s0, s10
	s_addc_u32 s1, s1, s11
	global_load_dwordx2 v[66:67], v1, s[0:1]
	s_add_u32 s0, s0, s10
	s_addc_u32 s1, s1, s11
	global_load_dwordx2 v[68:69], v1, s[0:1]
	s_add_u32 s0, s0, s10
	s_addc_u32 s1, s1, s11
	global_load_dwordx2 v[70:71], v1, s[0:1]
	s_add_u32 s0, s0, s10
	s_addc_u32 s1, s1, s11
	global_load_dwordx2 v[72:73], v1, s[0:1]
	s_add_u32 s0, s0, s10
	s_addc_u32 s1, s1, s11
	global_load_dwordx2 v[74:75], v1, s[0:1]
	s_add_u32 s0, s0, s10
	s_addc_u32 s1, s1, s11
	global_load_dwordx2 v[76:77], v1, s[0:1]
	s_add_u32 s0, s0, s10
	s_addc_u32 s1, s1, s11
	global_load_dwordx2 v[78:79], v1, s[0:1]
	s_add_u32 s0, s0, s10
	s_addc_u32 s1, s1, s11
	global_load_dwordx2 v[80:81], v1, s[0:1]
	s_add_u32 s0, s0, s10
	s_addc_u32 s1, s1, s11
	global_load_dwordx2 v[82:83], v1, s[0:1]
	s_add_u32 s0, s0, s10
	s_addc_u32 s1, s1, s11
	global_load_dwordx2 v[84:85], v1, s[0:1]
	s_add_u32 s0, s0, s10
	s_addc_u32 s1, s1, s11
	global_load_dwordx2 v[86:87], v1, s[0:1]
	s_add_u32 s0, s0, s10
	s_addc_u32 s1, s1, s11
	global_load_dwordx2 v[88:89], v1, s[0:1]
	s_add_u32 s0, s0, s10
	s_addc_u32 s1, s1, s11
	global_load_dwordx2 v[90:91], v1, s[0:1]
	s_add_u32 s0, s0, s10
	s_addc_u32 s1, s1, s11
	global_load_dwordx2 v[92:93], v1, s[0:1]
	s_add_u32 s0, s0, s10
	s_addc_u32 s1, s1, s11
	global_load_dwordx2 v[94:95], v1, s[0:1]
	s_add_u32 s0, s0, s10
	s_addc_u32 s1, s1, s11
	s_waitcnt vmcnt(32)
	v_cvt_pk_bf16_f32 v8, v6, v7
	global_store_dword v2, v8, s[8:9]
	s_add_u32 s8, s8, s10
	s_addc_u32 s9, s9, s11
	v_mul_f32_e32 v9, v5, v7
	v_mul_f32_e32 v10, v5, v6
	v_fma_f32 v9, v4, v6, -v9
	v_fma_f32 v10, v4, v7, v10
	v_add_f32_e32 v6, v9, v32
	v_add_f32_e32 v7, v10, v33
	v_cvt_pk_bf16_f32 v8, v6, v7
	global_store_dword v2, v8, s[8:9]
	s_add_u32 s8, s8, s10
	s_addc_u32 s9, s9, s11
	v_mul_f32_e32 v9, v5, v7
	v_mul_f32_e32 v10, v5, v6
	v_fma_f32 v9, v4, v6, -v9
	v_fma_f32 v10, v4, v7, v10
	v_add_f32_e32 v6, v9, v34
	v_add_f32_e32 v7, v10, v35
	v_cvt_pk_bf16_f32 v8, v6, v7
	global_store_dword v2, v8, s[8:9]
	s_add_u32 s8, s8, s10
	s_addc_u32 s9, s9, s11
	v_mul_f32_e32 v9, v5, v7
	v_mul_f32_e32 v10, v5, v6
	v_fma_f32 v9, v4, v6, -v9
	v_fma_f32 v10, v4, v7, v10
	v_add_f32_e32 v6, v9, v36
	v_add_f32_e32 v7, v10, v37
	v_cvt_pk_bf16_f32 v8, v6, v7
	global_store_dword v2, v8, s[8:9]
	s_add_u32 s8, s8, s10
	s_addc_u32 s9, s9, s11
	v_mul_f32_e32 v9, v5, v7
	v_mul_f32_e32 v10, v5, v6
	v_fma_f32 v9, v4, v6, -v9
	v_fma_f32 v10, v4, v7, v10
	v_add_f32_e32 v6, v9, v38
	v_add_f32_e32 v7, v10, v39
	v_cvt_pk_bf16_f32 v8, v6, v7
	global_store_dword v2, v8, s[8:9]
	s_add_u32 s8, s8, s10
	s_addc_u32 s9, s9, s11
	v_mul_f32_e32 v9, v5, v7
	v_mul_f32_e32 v10, v5, v6
	v_fma_f32 v9, v4, v6, -v9
	v_fma_f32 v10, v4, v7, v10
	v_add_f32_e32 v6, v9, v40
	v_add_f32_e32 v7, v10, v41
	v_cvt_pk_bf16_f32 v8, v6, v7
	global_store_dword v2, v8, s[8:9]
	s_add_u32 s8, s8, s10
	s_addc_u32 s9, s9, s11
	v_mul_f32_e32 v9, v5, v7
	v_mul_f32_e32 v10, v5, v6
	v_fma_f32 v9, v4, v6, -v9
	v_fma_f32 v10, v4, v7, v10
	v_add_f32_e32 v6, v9, v42
	v_add_f32_e32 v7, v10, v43
	v_cvt_pk_bf16_f32 v8, v6, v7
	global_store_dword v2, v8, s[8:9]
	s_add_u32 s8, s8, s10
	s_addc_u32 s9, s9, s11
	v_mul_f32_e32 v9, v5, v7
	v_mul_f32_e32 v10, v5, v6
	v_fma_f32 v9, v4, v6, -v9
	v_fma_f32 v10, v4, v7, v10
	v_add_f32_e32 v6, v9, v44
	v_add_f32_e32 v7, v10, v45
	v_cvt_pk_bf16_f32 v8, v6, v7
	global_store_dword v2, v8, s[8:9]
	s_add_u32 s8, s8, s10
	s_addc_u32 s9, s9, s11
	v_mul_f32_e32 v9, v5, v7
	v_mul_f32_e32 v10, v5, v6
	v_fma_f32 v9, v4, v6, -v9
	v_fma_f32 v10, v4, v7, v10
	v_add_f32_e32 v6, v9, v46
	v_add_f32_e32 v7, v10, v47
	v_cvt_pk_bf16_f32 v8, v6, v7
	global_store_dword v2, v8, s[8:9]
	s_add_u32 s8, s8, s10
	s_addc_u32 s9, s9, s11
	v_mul_f32_e32 v9, v5, v7
	v_mul_f32_e32 v10, v5, v6
	v_fma_f32 v9, v4, v6, -v9
	v_fma_f32 v10, v4, v7, v10
	v_add_f32_e32 v6, v9, v48
	v_add_f32_e32 v7, v10, v49
	v_cvt_pk_bf16_f32 v8, v6, v7
	global_store_dword v2, v8, s[8:9]
	s_add_u32 s8, s8, s10
	s_addc_u32 s9, s9, s11
	v_mul_f32_e32 v9, v5, v7
	v_mul_f32_e32 v10, v5, v6
	v_fma_f32 v9, v4, v6, -v9
	v_fma_f32 v10, v4, v7, v10
	v_add_f32_e32 v6, v9, v50
	v_add_f32_e32 v7, v10, v51
	v_cvt_pk_bf16_f32 v8, v6, v7
	global_store_dword v2, v8, s[8:9]
	s_add_u32 s8, s8, s10
	s_addc_u32 s9, s9, s11
	v_mul_f32_e32 v9, v5, v7
	v_mul_f32_e32 v10, v5, v6
	v_fma_f32 v9, v4, v6, -v9
	v_fma_f32 v10, v4, v7, v10
	v_add_f32_e32 v6, v9, v52
	v_add_f32_e32 v7, v10, v53
	v_cvt_pk_bf16_f32 v8, v6, v7
	global_store_dword v2, v8, s[8:9]
	s_add_u32 s8, s8, s10
	s_addc_u32 s9, s9, s11
	v_mul_f32_e32 v9, v5, v7
	v_mul_f32_e32 v10, v5, v6
	v_fma_f32 v9, v4, v6, -v9
	v_fma_f32 v10, v4, v7, v10
	v_add_f32_e32 v6, v9, v54
	v_add_f32_e32 v7, v10, v55
	v_cvt_pk_bf16_f32 v8, v6, v7
	global_store_dword v2, v8, s[8:9]
	s_add_u32 s8, s8, s10
	s_addc_u32 s9, s9, s11
	v_mul_f32_e32 v9, v5, v7
	v_mul_f32_e32 v10, v5, v6
	v_fma_f32 v9, v4, v6, -v9
	v_fma_f32 v10, v4, v7, v10
	v_add_f32_e32 v6, v9, v56
	v_add_f32_e32 v7, v10, v57
	v_cvt_pk_bf16_f32 v8, v6, v7
	global_store_dword v2, v8, s[8:9]
	s_add_u32 s8, s8, s10
	s_addc_u32 s9, s9, s11
	v_mul_f32_e32 v9, v5, v7
	v_mul_f32_e32 v10, v5, v6
	v_fma_f32 v9, v4, v6, -v9
	v_fma_f32 v10, v4, v7, v10
	v_add_f32_e32 v6, v9, v58
	v_add_f32_e32 v7, v10, v59
	v_cvt_pk_bf16_f32 v8, v6, v7
	global_store_dword v2, v8, s[8:9]
	s_add_u32 s8, s8, s10
	s_addc_u32 s9, s9, s11
	v_mul_f32_e32 v9, v5, v7
	v_mul_f32_e32 v10, v5, v6
	v_fma_f32 v9, v4, v6, -v9
	v_fma_f32 v10, v4, v7, v10
	v_add_f32_e32 v6, v9, v60
	v_add_f32_e32 v7, v10, v61
	v_cvt_pk_bf16_f32 v8, v6, v7
	global_store_dword v2, v8, s[8:9]
	s_add_u32 s8, s8, s10
	s_addc_u32 s9, s9, s11
	v_mul_f32_e32 v9, v5, v7
	v_mul_f32_e32 v10, v5, v6
	v_fma_f32 v9, v4, v6, -v9
	v_fma_f32 v10, v4, v7, v10
	v_add_f32_e32 v6, v9, v62
	v_add_f32_e32 v7, v10, v63
	global_load_dwordx2 v[96:97], v1, s[0:1]
	s_add_u32 s0, s0, s10
	s_addc_u32 s1, s1, s11
	global_load_dwordx2 v[98:99], v1, s[0:1]
	s_add_u32 s0, s0, s10
	s_addc_u32 s1, s1, s11
	global_load_dwordx2 v[100:101], v1, s[0:1]
	s_add_u32 s0, s0, s10
	s_addc_u32 s1, s1, s11
	global_load_dwordx2 v[102:103], v1, s[0:1]
	s_add_u32 s0, s0, s10
	s_addc_u32 s1, s1, s11
	global_load_dwordx2 v[104:105], v1, s[0:1]
	s_add_u32 s0, s0, s10
	s_addc_u32 s1, s1, s11
	global_load_dwordx2 v[106:107], v1, s[0:1]
	s_add_u32 s0, s0, s10
	s_addc_u32 s1, s1, s11
	global_load_dwordx2 v[108:109], v1, s[0:1]
	s_add_u32 s0, s0, s10
	s_addc_u32 s1, s1, s11
	global_load_dwordx2 v[110:111], v1, s[0:1]
	s_add_u32 s0, s0, s10
	s_addc_u32 s1, s1, s11
	global_load_dwordx2 v[112:113], v1, s[0:1]
	s_add_u32 s0, s0, s10
	s_addc_u32 s1, s1, s11
	global_load_dwordx2 v[114:115], v1, s[0:1]
	s_add_u32 s0, s0, s10
	s_addc_u32 s1, s1, s11
	global_load_dwordx2 v[116:117], v1, s[0:1]
	s_add_u32 s0, s0, s10
	s_addc_u32 s1, s1, s11
	global_load_dwordx2 v[118:119], v1, s[0:1]
	s_add_u32 s0, s0, s10
	s_addc_u32 s1, s1, s11
	global_load_dwordx2 v[120:121], v1, s[0:1]
	s_add_u32 s0, s0, s10
	s_addc_u32 s1, s1, s11
	global_load_dwordx2 v[122:123], v1, s[0:1]
	s_add_u32 s0, s0, s10
	s_addc_u32 s1, s1, s11
	global_load_dwordx2 v[124:125], v1, s[0:1]
	s_add_u32 s0, s0, s10
	s_addc_u32 s1, s1, s11
	global_load_dwordx2 v[126:127], v1, s[0:1]
	s_add_u32 s0, s0, s10
	s_addc_u32 s1, s1, s11
	s_waitcnt vmcnt(32)
	v_cvt_pk_bf16_f32 v8, v6, v7
	global_store_dword v2, v8, s[8:9]
	s_add_u32 s8, s8, s10
	s_addc_u32 s9, s9, s11
	v_mul_f32_e32 v9, v5, v7
	v_mul_f32_e32 v10, v5, v6
	v_fma_f32 v9, v4, v6, -v9
	v_fma_f32 v10, v4, v7, v10
	v_add_f32_e32 v6, v9, v64
	v_add_f32_e32 v7, v10, v65
	v_cvt_pk_bf16_f32 v8, v6, v7
	global_store_dword v2, v8, s[8:9]
	s_add_u32 s8, s8, s10
	s_addc_u32 s9, s9, s11
	v_mul_f32_e32 v9, v5, v7
	v_mul_f32_e32 v10, v5, v6
	v_fma_f32 v9, v4, v6, -v9
	v_fma_f32 v10, v4, v7, v10
	v_add_f32_e32 v6, v9, v66
	v_add_f32_e32 v7, v10, v67
	v_cvt_pk_bf16_f32 v8, v6, v7
	global_store_dword v2, v8, s[8:9]
	s_add_u32 s8, s8, s10
	s_addc_u32 s9, s9, s11
	v_mul_f32_e32 v9, v5, v7
	v_mul_f32_e32 v10, v5, v6
	v_fma_f32 v9, v4, v6, -v9
	v_fma_f32 v10, v4, v7, v10
	v_add_f32_e32 v6, v9, v68
	v_add_f32_e32 v7, v10, v69
	v_cvt_pk_bf16_f32 v8, v6, v7
	global_store_dword v2, v8, s[8:9]
	s_add_u32 s8, s8, s10
	s_addc_u32 s9, s9, s11
	v_mul_f32_e32 v9, v5, v7
	v_mul_f32_e32 v10, v5, v6
	v_fma_f32 v9, v4, v6, -v9
	v_fma_f32 v10, v4, v7, v10
	v_add_f32_e32 v6, v9, v70
	v_add_f32_e32 v7, v10, v71
	v_cvt_pk_bf16_f32 v8, v6, v7
	global_store_dword v2, v8, s[8:9]
	s_add_u32 s8, s8, s10
	s_addc_u32 s9, s9, s11
	v_mul_f32_e32 v9, v5, v7
	v_mul_f32_e32 v10, v5, v6
	v_fma_f32 v9, v4, v6, -v9
	v_fma_f32 v10, v4, v7, v10
	v_add_f32_e32 v6, v9, v72
	v_add_f32_e32 v7, v10, v73
	v_cvt_pk_bf16_f32 v8, v6, v7
	global_store_dword v2, v8, s[8:9]
	s_add_u32 s8, s8, s10
	s_addc_u32 s9, s9, s11
	v_mul_f32_e32 v9, v5, v7
	v_mul_f32_e32 v10, v5, v6
	v_fma_f32 v9, v4, v6, -v9
	v_fma_f32 v10, v4, v7, v10
	v_add_f32_e32 v6, v9, v74
	v_add_f32_e32 v7, v10, v75
	v_cvt_pk_bf16_f32 v8, v6, v7
	global_store_dword v2, v8, s[8:9]
	s_add_u32 s8, s8, s10
	s_addc_u32 s9, s9, s11
	v_mul_f32_e32 v9, v5, v7
	v_mul_f32_e32 v10, v5, v6
	v_fma_f32 v9, v4, v6, -v9
	v_fma_f32 v10, v4, v7, v10
	v_add_f32_e32 v6, v9, v76
	v_add_f32_e32 v7, v10, v77
	v_cvt_pk_bf16_f32 v8, v6, v7
	global_store_dword v2, v8, s[8:9]
	s_add_u32 s8, s8, s10
	s_addc_u32 s9, s9, s11
	v_mul_f32_e32 v9, v5, v7
	v_mul_f32_e32 v10, v5, v6
	v_fma_f32 v9, v4, v6, -v9
	v_fma_f32 v10, v4, v7, v10
	v_add_f32_e32 v6, v9, v78
	v_add_f32_e32 v7, v10, v79
	v_cvt_pk_bf16_f32 v8, v6, v7
	global_store_dword v2, v8, s[8:9]
	s_add_u32 s8, s8, s10
	s_addc_u32 s9, s9, s11
	v_mul_f32_e32 v9, v5, v7
	v_mul_f32_e32 v10, v5, v6
	v_fma_f32 v9, v4, v6, -v9
	v_fma_f32 v10, v4, v7, v10
	v_add_f32_e32 v6, v9, v80
	v_add_f32_e32 v7, v10, v81
	v_cvt_pk_bf16_f32 v8, v6, v7
	global_store_dword v2, v8, s[8:9]
	s_add_u32 s8, s8, s10
	s_addc_u32 s9, s9, s11
	v_mul_f32_e32 v9, v5, v7
	v_mul_f32_e32 v10, v5, v6
	v_fma_f32 v9, v4, v6, -v9
	v_fma_f32 v10, v4, v7, v10
	v_add_f32_e32 v6, v9, v82
	v_add_f32_e32 v7, v10, v83
	v_cvt_pk_bf16_f32 v8, v6, v7
	global_store_dword v2, v8, s[8:9]
	s_add_u32 s8, s8, s10
	s_addc_u32 s9, s9, s11
	v_mul_f32_e32 v9, v5, v7
	v_mul_f32_e32 v10, v5, v6
	v_fma_f32 v9, v4, v6, -v9
	v_fma_f32 v10, v4, v7, v10
	v_add_f32_e32 v6, v9, v84
	v_add_f32_e32 v7, v10, v85
	v_cvt_pk_bf16_f32 v8, v6, v7
	global_store_dword v2, v8, s[8:9]
	s_add_u32 s8, s8, s10
	s_addc_u32 s9, s9, s11
	v_mul_f32_e32 v9, v5, v7
	v_mul_f32_e32 v10, v5, v6
	v_fma_f32 v9, v4, v6, -v9
	v_fma_f32 v10, v4, v7, v10
	v_add_f32_e32 v6, v9, v86
	v_add_f32_e32 v7, v10, v87
	v_cvt_pk_bf16_f32 v8, v6, v7
	global_store_dword v2, v8, s[8:9]
	s_add_u32 s8, s8, s10
	s_addc_u32 s9, s9, s11
	v_mul_f32_e32 v9, v5, v7
	v_mul_f32_e32 v10, v5, v6
	v_fma_f32 v9, v4, v6, -v9
	v_fma_f32 v10, v4, v7, v10
	v_add_f32_e32 v6, v9, v88
	v_add_f32_e32 v7, v10, v89
	v_cvt_pk_bf16_f32 v8, v6, v7
	global_store_dword v2, v8, s[8:9]
	s_add_u32 s8, s8, s10
	s_addc_u32 s9, s9, s11
	v_mul_f32_e32 v9, v5, v7
	v_mul_f32_e32 v10, v5, v6
	v_fma_f32 v9, v4, v6, -v9
	v_fma_f32 v10, v4, v7, v10
	v_add_f32_e32 v6, v9, v90
	v_add_f32_e32 v7, v10, v91
	v_cvt_pk_bf16_f32 v8, v6, v7
	global_store_dword v2, v8, s[8:9]
	s_add_u32 s8, s8, s10
	s_addc_u32 s9, s9, s11
	v_mul_f32_e32 v9, v5, v7
	v_mul_f32_e32 v10, v5, v6
	v_fma_f32 v9, v4, v6, -v9
	v_fma_f32 v10, v4, v7, v10
	v_add_f32_e32 v6, v9, v92
	v_add_f32_e32 v7, v10, v93
	v_cvt_pk_bf16_f32 v8, v6, v7
	global_store_dword v2, v8, s[8:9]
	s_add_u32 s8, s8, s10
	s_addc_u32 s9, s9, s11
	v_mul_f32_e32 v9, v5, v7
	v_mul_f32_e32 v10, v5, v6
	v_fma_f32 v9, v4, v6, -v9
	v_fma_f32 v10, v4, v7, v10
	v_add_f32_e32 v6, v9, v94
	v_add_f32_e32 v7, v10, v95
	global_load_dwordx2 v[32:33], v1, s[0:1]
	s_add_u32 s0, s0, s10
	s_addc_u32 s1, s1, s11
	global_load_dwordx2 v[34:35], v1, s[0:1]
	s_add_u32 s0, s0, s10
	s_addc_u32 s1, s1, s11
	global_load_dwordx2 v[36:37], v1, s[0:1]
	s_add_u32 s0, s0, s10
	s_addc_u32 s1, s1, s11
	global_load_dwordx2 v[38:39], v1, s[0:1]
	s_add_u32 s0, s0, s10
	s_addc_u32 s1, s1, s11
	global_load_dwordx2 v[40:41], v1, s[0:1]
	s_add_u32 s0, s0, s10
	s_addc_u32 s1, s1, s11
	global_load_dwordx2 v[42:43], v1, s[0:1]
	s_add_u32 s0, s0, s10
	s_addc_u32 s1, s1, s11
	global_load_dwordx2 v[44:45], v1, s[0:1]
	s_add_u32 s0, s0, s10
	s_addc_u32 s1, s1, s11
	global_load_dwordx2 v[46:47], v1, s[0:1]
	s_add_u32 s0, s0, s10
	s_addc_u32 s1, s1, s11
	global_load_dwordx2 v[48:49], v1, s[0:1]
	s_add_u32 s0, s0, s10
	s_addc_u32 s1, s1, s11
	global_load_dwordx2 v[50:51], v1, s[0:1]
	s_add_u32 s0, s0, s10
	s_addc_u32 s1, s1, s11
	global_load_dwordx2 v[52:53], v1, s[0:1]
	s_add_u32 s0, s0, s10
	s_addc_u32 s1, s1, s11
	global_load_dwordx2 v[54:55], v1, s[0:1]
	s_add_u32 s0, s0, s10
	s_addc_u32 s1, s1, s11
	global_load_dwordx2 v[56:57], v1, s[0:1]
	s_add_u32 s0, s0, s10
	s_addc_u32 s1, s1, s11
	global_load_dwordx2 v[58:59], v1, s[0:1]
	s_add_u32 s0, s0, s10
	s_addc_u32 s1, s1, s11
	global_load_dwordx2 v[60:61], v1, s[0:1]
	s_add_u32 s0, s0, s10
	s_addc_u32 s1, s1, s11
	global_load_dwordx2 v[62:63], v1, s[0:1]
	s_add_u32 s0, s0, s10
	s_addc_u32 s1, s1, s11
	s_waitcnt vmcnt(32)
	v_cvt_pk_bf16_f32 v8, v6, v7
	global_store_dword v2, v8, s[8:9]
	s_add_u32 s8, s8, s10
	s_addc_u32 s9, s9, s11
	v_mul_f32_e32 v9, v5, v7
	v_mul_f32_e32 v10, v5, v6
	v_fma_f32 v9, v4, v6, -v9
	v_fma_f32 v10, v4, v7, v10
	v_add_f32_e32 v6, v9, v96
	v_add_f32_e32 v7, v10, v97
	v_cvt_pk_bf16_f32 v8, v6, v7
	global_store_dword v2, v8, s[8:9]
	s_add_u32 s8, s8, s10
	s_addc_u32 s9, s9, s11
	v_mul_f32_e32 v9, v5, v7
	v_mul_f32_e32 v10, v5, v6
	v_fma_f32 v9, v4, v6, -v9
	v_fma_f32 v10, v4, v7, v10
	v_add_f32_e32 v6, v9, v98
	v_add_f32_e32 v7, v10, v99
	v_cvt_pk_bf16_f32 v8, v6, v7
	global_store_dword v2, v8, s[8:9]
	s_add_u32 s8, s8, s10
	s_addc_u32 s9, s9, s11
	v_mul_f32_e32 v9, v5, v7
	v_mul_f32_e32 v10, v5, v6
	v_fma_f32 v9, v4, v6, -v9
	v_fma_f32 v10, v4, v7, v10
	v_add_f32_e32 v6, v9, v100
	v_add_f32_e32 v7, v10, v101
	v_cvt_pk_bf16_f32 v8, v6, v7
	global_store_dword v2, v8, s[8:9]
	s_add_u32 s8, s8, s10
	s_addc_u32 s9, s9, s11
	v_mul_f32_e32 v9, v5, v7
	v_mul_f32_e32 v10, v5, v6
	v_fma_f32 v9, v4, v6, -v9
	v_fma_f32 v10, v4, v7, v10
	v_add_f32_e32 v6, v9, v102
	v_add_f32_e32 v7, v10, v103
	v_cvt_pk_bf16_f32 v8, v6, v7
	global_store_dword v2, v8, s[8:9]
	s_add_u32 s8, s8, s10
	s_addc_u32 s9, s9, s11
	v_mul_f32_e32 v9, v5, v7
	v_mul_f32_e32 v10, v5, v6
	v_fma_f32 v9, v4, v6, -v9
	v_fma_f32 v10, v4, v7, v10
	v_add_f32_e32 v6, v9, v104
	v_add_f32_e32 v7, v10, v105
	v_cvt_pk_bf16_f32 v8, v6, v7
	global_store_dword v2, v8, s[8:9]
	s_add_u32 s8, s8, s10
	s_addc_u32 s9, s9, s11
	v_mul_f32_e32 v9, v5, v7
	v_mul_f32_e32 v10, v5, v6
	v_fma_f32 v9, v4, v6, -v9
	v_fma_f32 v10, v4, v7, v10
	v_add_f32_e32 v6, v9, v106
	v_add_f32_e32 v7, v10, v107
	v_cvt_pk_bf16_f32 v8, v6, v7
	global_store_dword v2, v8, s[8:9]
	s_add_u32 s8, s8, s10
	s_addc_u32 s9, s9, s11
	v_mul_f32_e32 v9, v5, v7
	v_mul_f32_e32 v10, v5, v6
	v_fma_f32 v9, v4, v6, -v9
	v_fma_f32 v10, v4, v7, v10
	v_add_f32_e32 v6, v9, v108
	v_add_f32_e32 v7, v10, v109
	v_cvt_pk_bf16_f32 v8, v6, v7
	global_store_dword v2, v8, s[8:9]
	s_add_u32 s8, s8, s10
	s_addc_u32 s9, s9, s11
	v_mul_f32_e32 v9, v5, v7
	v_mul_f32_e32 v10, v5, v6
	v_fma_f32 v9, v4, v6, -v9
	v_fma_f32 v10, v4, v7, v10
	v_add_f32_e32 v6, v9, v110
	v_add_f32_e32 v7, v10, v111
	v_cvt_pk_bf16_f32 v8, v6, v7
	global_store_dword v2, v8, s[8:9]
	s_add_u32 s8, s8, s10
	s_addc_u32 s9, s9, s11
	v_mul_f32_e32 v9, v5, v7
	v_mul_f32_e32 v10, v5, v6
	v_fma_f32 v9, v4, v6, -v9
	v_fma_f32 v10, v4, v7, v10
	v_add_f32_e32 v6, v9, v112
	v_add_f32_e32 v7, v10, v113
	v_cvt_pk_bf16_f32 v8, v6, v7
	global_store_dword v2, v8, s[8:9]
	s_add_u32 s8, s8, s10
	s_addc_u32 s9, s9, s11
	v_mul_f32_e32 v9, v5, v7
	v_mul_f32_e32 v10, v5, v6
	v_fma_f32 v9, v4, v6, -v9
	v_fma_f32 v10, v4, v7, v10
	v_add_f32_e32 v6, v9, v114
	v_add_f32_e32 v7, v10, v115
	v_cvt_pk_bf16_f32 v8, v6, v7
	global_store_dword v2, v8, s[8:9]
	s_add_u32 s8, s8, s10
	s_addc_u32 s9, s9, s11
	v_mul_f32_e32 v9, v5, v7
	v_mul_f32_e32 v10, v5, v6
	v_fma_f32 v9, v4, v6, -v9
	v_fma_f32 v10, v4, v7, v10
	v_add_f32_e32 v6, v9, v116
	v_add_f32_e32 v7, v10, v117
	v_cvt_pk_bf16_f32 v8, v6, v7
	global_store_dword v2, v8, s[8:9]
	s_add_u32 s8, s8, s10
	s_addc_u32 s9, s9, s11
	v_mul_f32_e32 v9, v5, v7
	v_mul_f32_e32 v10, v5, v6
	v_fma_f32 v9, v4, v6, -v9
	v_fma_f32 v10, v4, v7, v10
	v_add_f32_e32 v6, v9, v118
	v_add_f32_e32 v7, v10, v119
	v_cvt_pk_bf16_f32 v8, v6, v7
	global_store_dword v2, v8, s[8:9]
	s_add_u32 s8, s8, s10
	s_addc_u32 s9, s9, s11
	v_mul_f32_e32 v9, v5, v7
	v_mul_f32_e32 v10, v5, v6
	v_fma_f32 v9, v4, v6, -v9
	v_fma_f32 v10, v4, v7, v10
	v_add_f32_e32 v6, v9, v120
	v_add_f32_e32 v7, v10, v121
	v_cvt_pk_bf16_f32 v8, v6, v7
	global_store_dword v2, v8, s[8:9]
	s_add_u32 s8, s8, s10
	s_addc_u32 s9, s9, s11
	v_mul_f32_e32 v9, v5, v7
	v_mul_f32_e32 v10, v5, v6
	v_fma_f32 v9, v4, v6, -v9
	v_fma_f32 v10, v4, v7, v10
	v_add_f32_e32 v6, v9, v122
	v_add_f32_e32 v7, v10, v123
	v_cvt_pk_bf16_f32 v8, v6, v7
	global_store_dword v2, v8, s[8:9]
	s_add_u32 s8, s8, s10
	s_addc_u32 s9, s9, s11
	v_mul_f32_e32 v9, v5, v7
	v_mul_f32_e32 v10, v5, v6
	v_fma_f32 v9, v4, v6, -v9
	v_fma_f32 v10, v4, v7, v10
	v_add_f32_e32 v6, v9, v124
	v_add_f32_e32 v7, v10, v125
	v_cvt_pk_bf16_f32 v8, v6, v7
	global_store_dword v2, v8, s[8:9]
	s_add_u32 s8, s8, s10
	s_addc_u32 s9, s9, s11
	v_mul_f32_e32 v9, v5, v7
	v_mul_f32_e32 v10, v5, v6
	v_fma_f32 v9, v4, v6, -v9
	v_fma_f32 v10, v4, v7, v10
	v_add_f32_e32 v6, v9, v126
	v_add_f32_e32 v7, v10, v127
	global_load_dwordx2 v[64:65], v1, s[0:1]
	s_add_u32 s0, s0, s10
	s_addc_u32 s1, s1, s11
	global_load_dwordx2 v[66:67], v1, s[0:1]
	s_add_u32 s0, s0, s10
	s_addc_u32 s1, s1, s11
	global_load_dwordx2 v[68:69], v1, s[0:1]
	s_add_u32 s0, s0, s10
	s_addc_u32 s1, s1, s11
	global_load_dwordx2 v[70:71], v1, s[0:1]
	s_add_u32 s0, s0, s10
	s_addc_u32 s1, s1, s11
	global_load_dwordx2 v[72:73], v1, s[0:1]
	s_add_u32 s0, s0, s10
	s_addc_u32 s1, s1, s11
	global_load_dwordx2 v[74:75], v1, s[0:1]
	s_add_u32 s0, s0, s10
	s_addc_u32 s1, s1, s11
	global_load_dwordx2 v[76:77], v1, s[0:1]
	s_add_u32 s0, s0, s10
	s_addc_u32 s1, s1, s11
	global_load_dwordx2 v[78:79], v1, s[0:1]
	s_add_u32 s0, s0, s10
	s_addc_u32 s1, s1, s11
	global_load_dwordx2 v[80:81], v1, s[0:1]
	s_add_u32 s0, s0, s10
	s_addc_u32 s1, s1, s11
	global_load_dwordx2 v[82:83], v1, s[0:1]
	s_add_u32 s0, s0, s10
	s_addc_u32 s1, s1, s11
	global_load_dwordx2 v[84:85], v1, s[0:1]
	s_add_u32 s0, s0, s10
	s_addc_u32 s1, s1, s11
	global_load_dwordx2 v[86:87], v1, s[0:1]
	s_add_u32 s0, s0, s10
	s_addc_u32 s1, s1, s11
	global_load_dwordx2 v[88:89], v1, s[0:1]
	s_add_u32 s0, s0, s10
	s_addc_u32 s1, s1, s11
	global_load_dwordx2 v[90:91], v1, s[0:1]
	s_add_u32 s0, s0, s10
	s_addc_u32 s1, s1, s11
	global_load_dwordx2 v[92:93], v1, s[0:1]
	s_add_u32 s0, s0, s10
	s_addc_u32 s1, s1, s11
	global_load_dwordx2 v[94:95], v1, s[0:1]
	s_add_u32 s0, s0, s10
	s_addc_u32 s1, s1, s11
	s_waitcnt vmcnt(32)
	v_cvt_pk_bf16_f32 v8, v6, v7
	global_store_dword v2, v8, s[8:9]
	s_add_u32 s8, s8, s10
	s_addc_u32 s9, s9, s11
	v_mul_f32_e32 v9, v5, v7
	v_mul_f32_e32 v10, v5, v6
	v_fma_f32 v9, v4, v6, -v9
	v_fma_f32 v10, v4, v7, v10
	v_add_f32_e32 v6, v9, v32
	v_add_f32_e32 v7, v10, v33
	v_cvt_pk_bf16_f32 v8, v6, v7
	global_store_dword v2, v8, s[8:9]
	s_add_u32 s8, s8, s10
	s_addc_u32 s9, s9, s11
	v_mul_f32_e32 v9, v5, v7
	v_mul_f32_e32 v10, v5, v6
	v_fma_f32 v9, v4, v6, -v9
	v_fma_f32 v10, v4, v7, v10
	v_add_f32_e32 v6, v9, v34
	v_add_f32_e32 v7, v10, v35
	v_cvt_pk_bf16_f32 v8, v6, v7
	global_store_dword v2, v8, s[8:9]
	s_add_u32 s8, s8, s10
	s_addc_u32 s9, s9, s11
	v_mul_f32_e32 v9, v5, v7
	v_mul_f32_e32 v10, v5, v6
	v_fma_f32 v9, v4, v6, -v9
	v_fma_f32 v10, v4, v7, v10
	v_add_f32_e32 v6, v9, v36
	v_add_f32_e32 v7, v10, v37
	v_cvt_pk_bf16_f32 v8, v6, v7
	global_store_dword v2, v8, s[8:9]
	s_add_u32 s8, s8, s10
	s_addc_u32 s9, s9, s11
	v_mul_f32_e32 v9, v5, v7
	v_mul_f32_e32 v10, v5, v6
	v_fma_f32 v9, v4, v6, -v9
	v_fma_f32 v10, v4, v7, v10
	v_add_f32_e32 v6, v9, v38
	v_add_f32_e32 v7, v10, v39
	v_cvt_pk_bf16_f32 v8, v6, v7
	global_store_dword v2, v8, s[8:9]
	s_add_u32 s8, s8, s10
	s_addc_u32 s9, s9, s11
	v_mul_f32_e32 v9, v5, v7
	v_mul_f32_e32 v10, v5, v6
	v_fma_f32 v9, v4, v6, -v9
	v_fma_f32 v10, v4, v7, v10
	v_add_f32_e32 v6, v9, v40
	v_add_f32_e32 v7, v10, v41
	v_cvt_pk_bf16_f32 v8, v6, v7
	global_store_dword v2, v8, s[8:9]
	s_add_u32 s8, s8, s10
	s_addc_u32 s9, s9, s11
	v_mul_f32_e32 v9, v5, v7
	v_mul_f32_e32 v10, v5, v6
	v_fma_f32 v9, v4, v6, -v9
	v_fma_f32 v10, v4, v7, v10
	v_add_f32_e32 v6, v9, v42
	v_add_f32_e32 v7, v10, v43
	v_cvt_pk_bf16_f32 v8, v6, v7
	global_store_dword v2, v8, s[8:9]
	s_add_u32 s8, s8, s10
	s_addc_u32 s9, s9, s11
	v_mul_f32_e32 v9, v5, v7
	v_mul_f32_e32 v10, v5, v6
	v_fma_f32 v9, v4, v6, -v9
	v_fma_f32 v10, v4, v7, v10
	v_add_f32_e32 v6, v9, v44
	v_add_f32_e32 v7, v10, v45
	v_cvt_pk_bf16_f32 v8, v6, v7
	global_store_dword v2, v8, s[8:9]
	s_add_u32 s8, s8, s10
	s_addc_u32 s9, s9, s11
	v_mul_f32_e32 v9, v5, v7
	v_mul_f32_e32 v10, v5, v6
	v_fma_f32 v9, v4, v6, -v9
	v_fma_f32 v10, v4, v7, v10
	v_add_f32_e32 v6, v9, v46
	v_add_f32_e32 v7, v10, v47
	v_cvt_pk_bf16_f32 v8, v6, v7
	global_store_dword v2, v8, s[8:9]
	s_add_u32 s8, s8, s10
	s_addc_u32 s9, s9, s11
	v_mul_f32_e32 v9, v5, v7
	v_mul_f32_e32 v10, v5, v6
	v_fma_f32 v9, v4, v6, -v9
	v_fma_f32 v10, v4, v7, v10
	v_add_f32_e32 v6, v9, v48
	v_add_f32_e32 v7, v10, v49
	v_cvt_pk_bf16_f32 v8, v6, v7
	global_store_dword v2, v8, s[8:9]
	s_add_u32 s8, s8, s10
	s_addc_u32 s9, s9, s11
	v_mul_f32_e32 v9, v5, v7
	v_mul_f32_e32 v10, v5, v6
	v_fma_f32 v9, v4, v6, -v9
	v_fma_f32 v10, v4, v7, v10
	v_add_f32_e32 v6, v9, v50
	v_add_f32_e32 v7, v10, v51
	v_cvt_pk_bf16_f32 v8, v6, v7
	global_store_dword v2, v8, s[8:9]
	s_add_u32 s8, s8, s10
	s_addc_u32 s9, s9, s11
	v_mul_f32_e32 v9, v5, v7
	v_mul_f32_e32 v10, v5, v6
	v_fma_f32 v9, v4, v6, -v9
	v_fma_f32 v10, v4, v7, v10
	v_add_f32_e32 v6, v9, v52
	v_add_f32_e32 v7, v10, v53
	v_cvt_pk_bf16_f32 v8, v6, v7
	global_store_dword v2, v8, s[8:9]
	s_add_u32 s8, s8, s10
	s_addc_u32 s9, s9, s11
	v_mul_f32_e32 v9, v5, v7
	v_mul_f32_e32 v10, v5, v6
	v_fma_f32 v9, v4, v6, -v9
	v_fma_f32 v10, v4, v7, v10
	v_add_f32_e32 v6, v9, v54
	v_add_f32_e32 v7, v10, v55
	v_cvt_pk_bf16_f32 v8, v6, v7
	global_store_dword v2, v8, s[8:9]
	s_add_u32 s8, s8, s10
	s_addc_u32 s9, s9, s11
	v_mul_f32_e32 v9, v5, v7
	v_mul_f32_e32 v10, v5, v6
	v_fma_f32 v9, v4, v6, -v9
	v_fma_f32 v10, v4, v7, v10
	v_add_f32_e32 v6, v9, v56
	v_add_f32_e32 v7, v10, v57
	v_cvt_pk_bf16_f32 v8, v6, v7
	global_store_dword v2, v8, s[8:9]
	s_add_u32 s8, s8, s10
	s_addc_u32 s9, s9, s11
	v_mul_f32_e32 v9, v5, v7
	v_mul_f32_e32 v10, v5, v6
	v_fma_f32 v9, v4, v6, -v9
	v_fma_f32 v10, v4, v7, v10
	v_add_f32_e32 v6, v9, v58
	v_add_f32_e32 v7, v10, v59
	v_cvt_pk_bf16_f32 v8, v6, v7
	global_store_dword v2, v8, s[8:9]
	s_add_u32 s8, s8, s10
	s_addc_u32 s9, s9, s11
	v_mul_f32_e32 v9, v5, v7
	v_mul_f32_e32 v10, v5, v6
	v_fma_f32 v9, v4, v6, -v9
	v_fma_f32 v10, v4, v7, v10
	v_add_f32_e32 v6, v9, v60
	v_add_f32_e32 v7, v10, v61
	v_cvt_pk_bf16_f32 v8, v6, v7
	global_store_dword v2, v8, s[8:9]
	s_add_u32 s8, s8, s10
	s_addc_u32 s9, s9, s11
	v_mul_f32_e32 v9, v5, v7
	v_mul_f32_e32 v10, v5, v6
	v_fma_f32 v9, v4, v6, -v9
	v_fma_f32 v10, v4, v7, v10
	v_add_f32_e32 v6, v9, v62
	v_add_f32_e32 v7, v10, v63
	s_waitcnt vmcnt(16)
	v_cvt_pk_bf16_f32 v8, v6, v7
	global_store_dword v2, v8, s[8:9]
	s_add_u32 s8, s8, s10
	s_addc_u32 s9, s9, s11
	v_mul_f32_e32 v9, v5, v7
	v_mul_f32_e32 v10, v5, v6
	v_fma_f32 v9, v4, v6, -v9
	v_fma_f32 v10, v4, v7, v10
	v_add_f32_e32 v6, v9, v64
	v_add_f32_e32 v7, v10, v65
	v_cvt_pk_bf16_f32 v8, v6, v7
	global_store_dword v2, v8, s[8:9]
	s_add_u32 s8, s8, s10
	s_addc_u32 s9, s9, s11
	v_mul_f32_e32 v9, v5, v7
	v_mul_f32_e32 v10, v5, v6
	v_fma_f32 v9, v4, v6, -v9
	v_fma_f32 v10, v4, v7, v10
	v_add_f32_e32 v6, v9, v66
	v_add_f32_e32 v7, v10, v67
	v_cvt_pk_bf16_f32 v8, v6, v7
	global_store_dword v2, v8, s[8:9]
	s_add_u32 s8, s8, s10
	s_addc_u32 s9, s9, s11
	v_mul_f32_e32 v9, v5, v7
	v_mul_f32_e32 v10, v5, v6
	v_fma_f32 v9, v4, v6, -v9
	v_fma_f32 v10, v4, v7, v10
	v_add_f32_e32 v6, v9, v68
	v_add_f32_e32 v7, v10, v69
	v_cvt_pk_bf16_f32 v8, v6, v7
	global_store_dword v2, v8, s[8:9]
	s_add_u32 s8, s8, s10
	s_addc_u32 s9, s9, s11
	v_mul_f32_e32 v9, v5, v7
	v_mul_f32_e32 v10, v5, v6
	v_fma_f32 v9, v4, v6, -v9
	v_fma_f32 v10, v4, v7, v10
	v_add_f32_e32 v6, v9, v70
	v_add_f32_e32 v7, v10, v71
	v_cvt_pk_bf16_f32 v8, v6, v7
	global_store_dword v2, v8, s[8:9]
	s_add_u32 s8, s8, s10
	s_addc_u32 s9, s9, s11
	v_mul_f32_e32 v9, v5, v7
	v_mul_f32_e32 v10, v5, v6
	v_fma_f32 v9, v4, v6, -v9
	v_fma_f32 v10, v4, v7, v10
	v_add_f32_e32 v6, v9, v72
	v_add_f32_e32 v7, v10, v73
	v_cvt_pk_bf16_f32 v8, v6, v7
	global_store_dword v2, v8, s[8:9]
	s_add_u32 s8, s8, s10
	s_addc_u32 s9, s9, s11
	v_mul_f32_e32 v9, v5, v7
	v_mul_f32_e32 v10, v5, v6
	v_fma_f32 v9, v4, v6, -v9
	v_fma_f32 v10, v4, v7, v10
	v_add_f32_e32 v6, v9, v74
	v_add_f32_e32 v7, v10, v75
	v_cvt_pk_bf16_f32 v8, v6, v7
	global_store_dword v2, v8, s[8:9]
	s_add_u32 s8, s8, s10
	s_addc_u32 s9, s9, s11
	v_mul_f32_e32 v9, v5, v7
	v_mul_f32_e32 v10, v5, v6
	v_fma_f32 v9, v4, v6, -v9
	v_fma_f32 v10, v4, v7, v10
	v_add_f32_e32 v6, v9, v76
	v_add_f32_e32 v7, v10, v77
	v_cvt_pk_bf16_f32 v8, v6, v7
	global_store_dword v2, v8, s[8:9]
	s_add_u32 s8, s8, s10
	s_addc_u32 s9, s9, s11
	v_mul_f32_e32 v9, v5, v7
	v_mul_f32_e32 v10, v5, v6
	v_fma_f32 v9, v4, v6, -v9
	v_fma_f32 v10, v4, v7, v10
	v_add_f32_e32 v6, v9, v78
	v_add_f32_e32 v7, v10, v79
	v_cvt_pk_bf16_f32 v8, v6, v7
	global_store_dword v2, v8, s[8:9]
	s_add_u32 s8, s8, s10
	s_addc_u32 s9, s9, s11
	v_mul_f32_e32 v9, v5, v7
	v_mul_f32_e32 v10, v5, v6
	v_fma_f32 v9, v4, v6, -v9
	v_fma_f32 v10, v4, v7, v10
	v_add_f32_e32 v6, v9, v80
	v_add_f32_e32 v7, v10, v81
	v_cvt_pk_bf16_f32 v8, v6, v7
	global_store_dword v2, v8, s[8:9]
	s_add_u32 s8, s8, s10
	s_addc_u32 s9, s9, s11
	v_mul_f32_e32 v9, v5, v7
	v_mul_f32_e32 v10, v5, v6
	v_fma_f32 v9, v4, v6, -v9
	v_fma_f32 v10, v4, v7, v10
	v_add_f32_e32 v6, v9, v82
	v_add_f32_e32 v7, v10, v83
	v_cvt_pk_bf16_f32 v8, v6, v7
	global_store_dword v2, v8, s[8:9]
	s_add_u32 s8, s8, s10
	s_addc_u32 s9, s9, s11
	v_mul_f32_e32 v9, v5, v7
	v_mul_f32_e32 v10, v5, v6
	v_fma_f32 v9, v4, v6, -v9
	v_fma_f32 v10, v4, v7, v10
	v_add_f32_e32 v6, v9, v84
	v_add_f32_e32 v7, v10, v85
	v_cvt_pk_bf16_f32 v8, v6, v7
	global_store_dword v2, v8, s[8:9]
	s_add_u32 s8, s8, s10
	s_addc_u32 s9, s9, s11
	v_mul_f32_e32 v9, v5, v7
	v_mul_f32_e32 v10, v5, v6
	v_fma_f32 v9, v4, v6, -v9
	v_fma_f32 v10, v4, v7, v10
	v_add_f32_e32 v6, v9, v86
	v_add_f32_e32 v7, v10, v87
	v_cvt_pk_bf16_f32 v8, v6, v7
	global_store_dword v2, v8, s[8:9]
	s_add_u32 s8, s8, s10
	s_addc_u32 s9, s9, s11
	v_mul_f32_e32 v9, v5, v7
	v_mul_f32_e32 v10, v5, v6
	v_fma_f32 v9, v4, v6, -v9
	v_fma_f32 v10, v4, v7, v10
	v_add_f32_e32 v6, v9, v88
	v_add_f32_e32 v7, v10, v89
	v_cvt_pk_bf16_f32 v8, v6, v7
	global_store_dword v2, v8, s[8:9]
	s_add_u32 s8, s8, s10
	s_addc_u32 s9, s9, s11
	v_mul_f32_e32 v9, v5, v7
	v_mul_f32_e32 v10, v5, v6
	v_fma_f32 v9, v4, v6, -v9
	v_fma_f32 v10, v4, v7, v10
	v_add_f32_e32 v6, v9, v90
	v_add_f32_e32 v7, v10, v91
	v_cvt_pk_bf16_f32 v8, v6, v7
	global_store_dword v2, v8, s[8:9]
	s_add_u32 s8, s8, s10
	s_addc_u32 s9, s9, s11
	v_mul_f32_e32 v9, v5, v7
	v_mul_f32_e32 v10, v5, v6
	v_fma_f32 v9, v4, v6, -v9
	v_fma_f32 v10, v4, v7, v10
	v_add_f32_e32 v6, v9, v92
	v_add_f32_e32 v7, v10, v93
	v_cvt_pk_bf16_f32 v8, v6, v7
	global_store_dword v2, v8, s[8:9]
	s_add_u32 s8, s8, s10
	s_addc_u32 s9, s9, s11
	v_mul_f32_e32 v9, v5, v7
	v_mul_f32_e32 v10, v5, v6
	v_fma_f32 v9, v4, v6, -v9
	v_fma_f32 v10, v4, v7, v10
	v_add_f32_e32 v6, v9, v94
	v_add_f32_e32 v7, v10, v95
	s_branch .Lscan_end

.LBB0_1418:
	s_cmp_lt_i32 s40, 14
	s_cselect_b64 s[22:23], -1, 0
	s_and_b64 s[0:1], s[0:1], s[22:23]
	s_andn2_b64 vcc, exec, s[0:1]
	s_cbranch_vccnz .LBB0_1726
	v_mov_b32_e32 v129, 0
	s_lshr_b32 s70, s93, 8
	s_lshl_b32 s3, s94, 10
	s_cmpk_lt_i32 s2, 0x60
	s_cselect_b64 s[62:63], -1, 0
	s_cmpk_gt_i32 s2, 0x5f
	v_mbcnt_lo_u32_b32 v8, -1, 0
	v_mbcnt_hi_u32_b32 v8, -1, v8
	s_waitcnt vmcnt(0)
	v_readlane_b32 s13, v246, 21
	v_readlane_b32 s12, v246, 20
	s_cbranch_scc1 .LBB0_1435
	v_lshl_add_u32 v0, v8, 4, s3
	v_add_u32_e32 v1, 0x2000, v0
	v_ashrrev_i32_e32 v2, 31, v1
	v_lshrrev_b32_e32 v2, 22, v2
	v_add_u32_e32 v2, v1, v2
	v_ashrrev_i32_e32 v9, 10, v2
	v_mul_i32_i24_e32 v2, 0x400, v9
	v_sub_u32_e32 v1, v1, v2
	v_lshrrev_b32_e32 v2, 4, v1
	v_bitop3_b32 v1, v2, v1, 32 bitop3:0x6c
	v_ashrrev_i32_e32 v2, 31, v1
	v_lshrrev_b32_e32 v2, 26, v2
	s_cmp_eq_u32 s70, 1
	v_add_u32_e32 v2, v1, v2
	s_cselect_b64 s[14:15], -1, 0
	s_ashr_i32 s71, s2, 31
	v_ashrrev_i32_e32 v10, 6, v2
	v_lshlrev_b32_e32 v3, 3, v9
	v_and_b32_e32 v2, 0xffc0, v2
	s_lshr_b32 s0, s71, 29
	v_and_b32_e32 v3, -16, v3
	v_sub_u32_e32 v1, v1, v2
	s_add_i32 s0, s2, s0
	v_add_u32_e32 v3, v10, v3
	v_lshrrev_b16_e32 v2, 7, v1
	s_ashr_i32 s1, s0, 3
	s_and_b32 s0, s0, -8
	v_and_b32_e32 v4, 3, v10
	s_mov_b32 s19, 0x3fffe0
	v_lshrrev_b32_e32 v5, 2, v3
	v_lshlrev_b32_e32 v6, 1, v3
	v_and_b32_e32 v2, 1, v2
	s_sub_i32 s0, s2, s0
	v_and_or_b32 v4, v3, s19, v4
	v_and_b32_e32 v5, 4, v5
	v_and_b32_e32 v6, 24, v6
	v_add_u16_e32 v1, v1, v2
	v_mov_b32_e32 v2, 1
	s_cmp_lt_i32 s0, 0
	v_or3_b32 v4, v4, v5, v6
	v_lshlrev_b32_e32 v5, 5, v9
	v_ashrrev_i16_sdwa v1, v2, sext(v1) dst_sel:DWORD dst_unused:UNUSED_PAD src0_sel:DWORD src1_sel:BYTE_0
	s_cselect_b32 s4, 13, 12
	v_and_b32_e32 v5, 32, v5
	v_bfe_i32 v11, v1, 0, 16
	s_mul_i32 s0, s0, s4
	v_add_lshl_u32 v1, v5, v11, 1
	s_add_i32 s0, s0, s1
	v_lshl_add_u32 v130, v4, 10, v1
	v_lshl_add_u32 v132, v3, 10, v1
	v_ashrrev_i32_e32 v1, 31, v0
	s_ashr_i32 s1, s0, 31
	v_lshrrev_b32_e32 v1, 22, v1
	s_lshr_b32 s1, s1, 28
	v_add_u32_e32 v1, v0, v1
	s_add_i32 s1, s0, s1
	v_ashrrev_i32_e32 v12, 10, v1
	s_ashr_i32 s4, s1, 4
	s_and_b32 s1, s1, -16
	v_mul_i32_i24_e32 v1, 0x400, v12
	s_sub_i32 s0, s0, s1
	v_sub_u32_e32 v0, v0, v1
	s_bfe_i32 s1, s0, 0x80000
	v_lshrrev_b32_e32 v1, 4, v0
	s_bfe_u32 s1, s1, 0x3000c
	v_bitop3_b32 v0, v1, v0, 32 bitop3:0x6c
	s_add_i32 s1, s0, s1
	v_ashrrev_i32_e32 v1, 31, v0
	s_lshl_b32 s5, s4, 3
	s_bfe_i32 s4, s1, 0x80000
	s_and_b32 s1, s1, 0xf8
	v_lshrrev_b32_e32 v1, 26, v1
	s_sub_i32 s0, s0, s1
	v_add_u32_e32 v1, v0, v1
	v_lshlrev_b32_e32 v3, 3, v12
	s_sext_i32_i16 s4, s4
	s_sext_i32_i8 s0, s0
	v_ashrrev_i32_e32 v13, 6, v1
	v_and_b32_e32 v3, -16, v3
	s_lshr_b32 s4, s4, 3
	s_add_i32 s0, s5, s0
	v_add_u32_e32 v3, v13, v3
	s_ashr_i32 s1, s0, 31
	s_bfe_i64 s[8:9], s[4:5], 0x100000
	v_and_b32_e32 v4, 3, v13
	v_lshrrev_b32_e32 v5, 2, v3
	v_lshlrev_b32_e32 v6, 1, v3
	v_and_b32_e32 v1, 0xc0, v1
	s_lshl_b64 s[6:7], s[0:1], 18
	s_lshl_b64 s[8:9], s[8:9], 18
	v_and_or_b32 v4, v3, s19, v4
	v_and_b32_e32 v5, 4, v5
	v_and_b32_e32 v6, 24, v6
	v_sub_u32_e32 v0, v0, v1
	s_add_u32 s8, s36, s8
	v_or3_b32 v4, v4, v5, v6
	v_lshlrev_b32_e32 v5, 5, v12
	v_ashrrev_i16_sdwa v0, v2, sext(v0) dst_sel:DWORD dst_unused:UNUSED_PAD src0_sel:DWORD src1_sel:BYTE_0
	s_addc_u32 s9, s37, s9
	s_add_i32 s72, s3, 0
	v_and_b32_e32 v5, 32, v5
	v_bfe_i32 v14, v0, 0, 16
	s_add_i32 m0, s72, 0x10000
	s_add_i32 s1, s72, 0x12000
	v_add_lshl_u32 v0, v5, v14, 1
	s_add_u32 s16, s8, 0x20000
	v_lshl_add_u32 v128, v4, 10, v0
	s_addc_u32 s17, s9, 0
	s_add_i32 s5, s72, 0x14000
	s_add_i32 s18, s72, 0x16000
	global_load_lds_dwordx4 v128, s[8:9]
	s_mov_b32 m0, s1
	s_add_u32 s6, s60, s6
	global_load_lds_dwordx4 v130, s[8:9]
	s_mov_b32 m0, s5
	s_addc_u32 s7, s61, s7
	s_add_i32 s73, s72, 0x2000
	global_load_lds_dwordx4 v128, s[16:17]
	s_mov_b32 m0, s18
	s_add_u32 s10, s6, 0x20000
	v_lshl_add_u32 v134, v3, 10, v0
	global_load_lds_dwordx4 v130, s[16:17]
	s_mov_b32 m0, s72
	s_addc_u32 s11, s7, 0
	s_add_i32 s74, s72, 0x4000
	global_load_lds_dwordx4 v134, s[6:7]
	s_mov_b32 m0, s73
	s_add_i32 s75, s72, 0x6000
	global_load_lds_dwordx4 v132, s[6:7]
	s_mov_b32 m0, s74
	v_mov_b32_e32 v131, v129
	global_load_lds_dwordx4 v134, s[10:11]
	s_mov_b32 m0, s75
	v_mov_b32_e32 v135, v129
	global_load_lds_dwordx4 v132, s[10:11]
	v_mov_b32_e32 v133, v129
	s_mov_b32 s76, 0
	s_cmp_lg_u32 s70, 1
	v_lshl_add_u64 v[6:7], s[8:9], 0, v[128:129]
	v_lshl_add_u64 v[4:5], s[8:9], 0, v[130:131]
	v_lshl_add_u64 v[2:3], s[6:7], 0, v[134:135]
	v_lshl_add_u64 v[0:1], s[6:7], 0, v[132:133]
	s_cbranch_scc1 .LBB0_1422
	s_barrier

.LBB0_1776:
	s_cmp_lt_i32 s40, 15
	s_cselect_b64 s[12:13], -1, 0
	s_and_b64 s[0:1], s[0:1], s[12:13]
	s_andn2_b64 vcc, exec, s[0:1]
	s_cbranch_vccnz .LBB0_1822
	v_mov_b32_e32 v153, 0
	s_cmpk_gt_i32 s2, 0xbf
	v_mbcnt_lo_u32_b32 v8, -1, 0
	v_mbcnt_hi_u32_b32 v8, -1, v8
	s_waitcnt vmcnt(0)
	v_readlane_b32 s9, v246, 23
	v_readlane_b32 s10, v246, 22
	s_cbranch_scc1 .LBB0_1822
	s_lshl_b32 s3, s94, 10
	v_lshlrev_b32_e32 v12, 4, v8
	v_add_u32_e32 v0, s3, v12
	v_add_u32_e32 v1, 0x2000, v0
	v_ashrrev_i32_e32 v2, 31, v1
	v_lshrrev_b32_e32 v2, 22, v2
	v_add_u32_e32 v2, v1, v2
	v_ashrrev_i32_e32 v9, 10, v2
	v_mul_i32_i24_e32 v2, 0x400, v9
	v_sub_u32_e32 v1, v1, v2
	v_lshrrev_b32_e32 v2, 4, v1
	v_bitop3_b32 v1, v2, v1, 32 bitop3:0x6c
	v_ashrrev_i32_e32 v2, 31, v1
	v_lshrrev_b32_e32 v2, 26, v2
	v_add_u32_e32 v2, v1, v2
	v_ashrrev_i32_e32 v10, 6, v2
	v_lshlrev_b32_e32 v3, 3, v9
	v_and_b32_e32 v2, 0xffc0, v2
	v_and_b32_e32 v3, -16, v3
	v_sub_u32_e32 v1, v1, v2
	v_add_u32_e32 v3, v10, v3
	v_lshrrev_b16_e32 v2, 7, v1
	v_and_b32_e32 v4, 3, v10
	s_mov_b32 s17, 0x1fffe0
	v_lshrrev_b32_e32 v5, 2, v3
	v_lshlrev_b32_e32 v6, 1, v3
	v_and_b32_e32 v2, 1, v2
	v_and_or_b32 v4, v3, s17, v4
	v_and_b32_e32 v5, 4, v5
	v_and_b32_e32 v6, 24, v6
	v_add_u16_e32 v1, v1, v2
	v_mov_b32_e32 v2, 1
	v_or3_b32 v4, v4, v5, v6
	v_lshlrev_b32_e32 v5, 5, v9
	v_ashrrev_i16_sdwa v1, v2, sext(v1) dst_sel:DWORD dst_unused:UNUSED_PAD src0_sel:DWORD src1_sel:BYTE_0
	v_and_b32_e32 v5, 32, v5
	v_bfe_i32 v11, v1, 0, 16
	v_add_lshl_u32 v1, v5, v11, 1
	v_lshl_add_u32 v154, v4, 11, v1
	v_lshl_add_u32 v156, v3, 11, v1
	v_ashrrev_i32_e32 v1, 31, v0
	v_lshrrev_b32_e32 v1, 22, v1
	v_add_u32_e32 v1, v0, v1
	v_ashrrev_i32_e32 v13, 10, v1
	v_mul_i32_i24_e32 v1, 0x400, v13
	v_sub_u32_e32 v0, v0, v1
	v_lshrrev_b32_e32 v1, 4, v0
	v_bitop3_b32 v0, v1, v0, 32 bitop3:0x6c
	v_ashrrev_i32_e32 v1, 31, v0
	s_ashr_i32 s1, s2, 2
	v_lshrrev_b32_e32 v1, 26, v1
	s_and_b32 s0, s2, 7
	s_and_b32 s1, s1, -8
	v_add_u32_e32 v1, v0, v1
	v_lshlrev_b32_e32 v3, 3, v13
	s_lshr_b32 s8, s93, 8
	s_or_b32 s0, s1, s0
	s_bfe_u32 s68, s2, 0x20003
	v_ashrrev_i32_e32 v14, 6, v1
	v_and_b32_e32 v3, -16, v3
	s_cmp_eq_u32 s8, 1
	v_add_u32_e32 v3, v14, v3
	s_cselect_b64 s[14:15], -1, 0
	s_ashr_i32 s1, s0, 31
	v_and_b32_e32 v4, 3, v14
	v_lshrrev_b32_e32 v5, 2, v3
	v_lshlrev_b32_e32 v6, 1, v3
	v_and_b32_e32 v1, 0xc0, v1
	s_lshl_b64 s[4:5], s[0:1], 19
	s_lshl_b32 s1, s68, 19
	v_and_or_b32 v4, v3, s17, v4
	v_and_b32_e32 v5, 4, v5
	v_and_b32_e32 v6, 24, v6
	v_sub_u32_e32 v0, v0, v1
	s_add_u32 s72, s26, s1
	v_or3_b32 v4, v4, v5, v6
	v_lshlrev_b32_e32 v5, 5, v13
	v_ashrrev_i16_sdwa v0, v2, sext(v0) dst_sel:DWORD dst_unused:UNUSED_PAD src0_sel:DWORD src1_sel:BYTE_0
	s_addc_u32 s73, s27, 0
	s_add_i32 s24, s3, 0
	v_and_b32_e32 v5, 32, v5
	v_bfe_i32 v15, v0, 0, 16
	s_add_i32 m0, s24, 0x10000
	s_add_i32 s1, s24, 0x12000
	v_add_lshl_u32 v0, v5, v15, 1
	s_add_u32 s6, s72, 0x40000
	v_lshl_add_u32 v152, v4, 11, v0
	s_addc_u32 s7, s73, 0
	s_add_i32 s11, s24, 0x14000
	s_add_i32 s16, s24, 0x16000
	global_load_lds_dwordx4 v152, s[72:73]
	s_mov_b32 m0, s1
	s_add_u32 s70, s48, s4
	global_load_lds_dwordx4 v154, s[72:73]
	s_mov_b32 m0, s11
	s_addc_u32 s71, s49, s5
	s_add_i32 s25, s24, 0x2000
	global_load_lds_dwordx4 v152, s[6:7]
	s_mov_b32 m0, s16
	s_add_u32 s4, s70, 0x40000
	v_lshl_add_u32 v158, v3, 11, v0
	global_load_lds_dwordx4 v154, s[6:7]
	s_mov_b32 m0, s24
	s_addc_u32 s5, s71, 0
	s_add_i32 s33, s24, 0x4000
	global_load_lds_dwordx4 v158, s[70:71]
	s_mov_b32 m0, s25
	s_add_i32 s42, s24, 0x6000
	global_load_lds_dwordx4 v156, s[70:71]
	s_mov_b32 m0, s33
	v_mov_b32_e32 v155, v153
	global_load_lds_dwordx4 v158, s[4:5]
	s_mov_b32 m0, s42
	v_mov_b32_e32 v159, v153
	global_load_lds_dwordx4 v156, s[4:5]
	v_mov_b32_e32 v157, v153
	s_mov_b32 s17, 0
	s_cmp_lg_u32 s8, 1
	v_lshl_add_u64 v[6:7], s[72:73], 0, v[152:153]
	v_lshl_add_u64 v[4:5], s[72:73], 0, v[154:155]
	v_lshl_add_u64 v[2:3], s[70:71], 0, v[158:159]
	v_lshl_add_u64 v[0:1], s[70:71], 0, v[156:157]
	s_cbranch_scc1 .LBB0_1780
	s_barrier

.LBB0_1939:
	s_cmp_gt_i32 s40, 17
	s_cselect_b64 s[0:1], -1, 0
	s_xor_b64 s[4:5], s[4:5], -1
	s_or_b64 s[0:1], s[4:5], s[0:1]
	s_and_b64 vcc, exec, s[0:1]
	s_cbranch_vccnz .LBB0_1985
	v_mov_b32_e32 v153, 0
	s_cmpk_gt_i32 s2, 0xbf
	v_mbcnt_lo_u32_b32 v8, -1, 0
	v_mbcnt_hi_u32_b32 v8, -1, v8
	s_waitcnt vmcnt(0)
	v_readlane_b32 s13, v246, 25
	v_readlane_b32 s12, v246, 24
	s_cbranch_scc1 .LBB0_1985
	s_lshl_b32 s3, s94, 10
	v_lshlrev_b32_e32 v12, 4, v8
	v_add_u32_e32 v0, s3, v12
	v_add_u32_e32 v1, 0x2000, v0
	v_ashrrev_i32_e32 v2, 31, v1
	v_lshrrev_b32_e32 v2, 22, v2
	v_add_u32_e32 v2, v1, v2
	v_ashrrev_i32_e32 v9, 10, v2
	v_mul_i32_i24_e32 v2, 0x400, v9
	v_sub_u32_e32 v1, v1, v2
	v_lshrrev_b32_e32 v2, 4, v1
	v_bitop3_b32 v1, v2, v1, 32 bitop3:0x6c
	v_ashrrev_i32_e32 v2, 31, v1
	s_ashr_i32 s1, s2, 2
	v_lshrrev_b32_e32 v2, 26, v2
	s_and_b32 s0, s2, 7
	s_and_b32 s1, s1, -8
	v_add_u32_e32 v2, v1, v2
	s_lshr_b32 s6, s93, 8
	s_or_b32 s10, s1, s0
	s_bfe_u32 s50, s2, 0x20003
	v_ashrrev_i32_e32 v10, 6, v2
	v_lshlrev_b32_e32 v3, 3, v9
	v_and_b32_e32 v2, 0xffc0, v2
	s_cmp_eq_u32 s6, 1
	v_and_b32_e32 v3, -16, v3
	v_sub_u32_e32 v1, v1, v2
	s_cselect_b64 s[14:15], -1, 0
	s_ashr_i32 s11, s10, 31
	v_add_u32_e32 v3, v10, v3
	v_lshrrev_b16_e32 v2, 7, v1
	s_lshl_b64 s[0:1], s[10:11], 21
	v_and_b32_e32 v4, 3, v10
	s_mov_b32 s11, 0x7ffe0
	v_lshrrev_b32_e32 v5, 2, v3
	v_lshlrev_b32_e32 v6, 1, v3
	v_and_b32_e32 v2, 1, v2
	v_and_or_b32 v4, v3, s11, v4
	v_and_b32_e32 v5, 4, v5
	v_and_b32_e32 v6, 24, v6
	v_add_u16_e32 v1, v1, v2
	v_mov_b32_e32 v2, 1
	v_or3_b32 v4, v4, v5, v6
	v_lshlrev_b32_e32 v5, 5, v9
	v_ashrrev_i16_sdwa v1, v2, sext(v1) dst_sel:DWORD dst_unused:UNUSED_PAD src0_sel:DWORD src1_sel:BYTE_0
	v_and_b32_e32 v5, 32, v5
	v_bfe_i32 v11, v1, 0, 16
	v_add_lshl_u32 v1, v5, v11, 1
	v_lshl_add_u32 v154, v4, 13, v1
	v_lshl_add_u32 v156, v3, 13, v1
	v_ashrrev_i32_e32 v1, 31, v0
	v_lshrrev_b32_e32 v1, 22, v1
	v_add_u32_e32 v1, v0, v1
	v_ashrrev_i32_e32 v13, 10, v1
	v_mul_i32_i24_e32 v1, 0x400, v13
	v_sub_u32_e32 v0, v0, v1
	v_lshrrev_b32_e32 v1, 4, v0
	v_bitop3_b32 v0, v1, v0, 32 bitop3:0x6c
	v_ashrrev_i32_e32 v1, 31, v0
	v_lshrrev_b32_e32 v1, 26, v1
	v_add_u32_e32 v1, v0, v1
	v_lshlrev_b32_e32 v3, 3, v13
	v_ashrrev_i32_e32 v14, 6, v1
	v_and_b32_e32 v3, -16, v3
	v_add_u32_e32 v3, v14, v3
	v_and_b32_e32 v4, 3, v14
	v_lshrrev_b32_e32 v5, 2, v3
	v_lshlrev_b32_e32 v6, 1, v3
	v_and_b32_e32 v1, 0xc0, v1
	s_lshl_b32 s4, s50, 21
	v_and_or_b32 v4, v3, s11, v4
	v_and_b32_e32 v5, 4, v5
	v_and_b32_e32 v6, 24, v6
	v_sub_u32_e32 v0, v0, v1
	s_add_u32 s58, s28, s4
	v_or3_b32 v4, v4, v5, v6
	v_lshlrev_b32_e32 v5, 5, v13
	v_ashrrev_i16_sdwa v0, v2, sext(v0) dst_sel:DWORD dst_unused:UNUSED_PAD src0_sel:DWORD src1_sel:BYTE_0
	s_addc_u32 s59, s29, 0
	s_add_i32 s33, s3, 0
	v_and_b32_e32 v5, 32, v5
	v_bfe_i32 v15, v0, 0, 16
	s_add_i32 m0, s33, 0x10000
	s_add_i32 s7, s33, 0x12000
	v_add_lshl_u32 v0, v5, v15, 1
	s_add_u32 s4, s58, 0x100000
	v_lshl_add_u32 v152, v4, 13, v0
	s_addc_u32 s5, s59, 0
	s_add_i32 s8, s33, 0x14000
	s_add_i32 s9, s33, 0x16000
	global_load_lds_dwordx4 v152, s[58:59]
	s_mov_b32 m0, s7
	s_add_u32 s60, s44, s0
	global_load_lds_dwordx4 v154, s[58:59]
	s_mov_b32 m0, s8
	s_addc_u32 s61, s45, s1
	s_add_i32 s57, s33, 0x2000
	global_load_lds_dwordx4 v152, s[4:5]
	s_mov_b32 m0, s9
	s_add_u32 s0, s60, 0x100000
	v_lshl_add_u32 v158, v3, 13, v0
	global_load_lds_dwordx4 v154, s[4:5]
	s_mov_b32 m0, s33
	s_addc_u32 s1, s61, 0
	s_add_i32 s62, s33, 0x4000
	global_load_lds_dwordx4 v158, s[60:61]
	s_mov_b32 m0, s57
	s_add_i32 s63, s33, 0x6000
	global_load_lds_dwordx4 v156, s[60:61]
	s_mov_b32 m0, s62
	v_mov_b32_e32 v155, v153
	global_load_lds_dwordx4 v158, s[0:1]
	s_mov_b32 m0, s63
	v_mov_b32_e32 v159, v153
	global_load_lds_dwordx4 v156, s[0:1]
	v_mov_b32_e32 v157, v153
	s_mov_b32 s17, 0
	s_cmp_lg_u32 s6, 1
	v_lshl_add_u64 v[6:7], s[58:59], 0, v[152:153]
	v_lshl_add_u64 v[4:5], s[58:59], 0, v[154:155]
	v_lshl_add_u64 v[2:3], s[60:61], 0, v[158:159]
	v_lshl_add_u64 v[0:1], s[60:61], 0, v[156:157]
	s_cbranch_scc1 .LBB0_1943
	s_barrier
